# G1 epilogue row scales prefetched before the K-loop; RG-LRU carry scan spread over the 32 HGRN2 chain WGs (one wave each) after their chain
# speedup vs baseline: 1.0224x; 1.0134x over previous
.LBB0_669:
	s_xor_b64 s[12:13], s[42:43], -1
	s_and_b64 s[42:43], s[42:43], exec
	s_cselect_b32 s11, s9, s39
	s_cselect_b32 s17, s8, s38
	s_cselect_b32 s23, s7, s41
	s_cselect_b32 s44, s6, s40
	s_add_u32 s38, s38, 0x40080
	s_addc_u32 s39, s39, 0
	s_add_u32 s45, s40, 0x100
	v_mov_b32_e32 v0, 0
	s_addc_u32 s52, s41, 0
	s_mov_b32 s53, -2
	v_readlane_b32 vcc_lo, v252, 38
	v_readlane_b32 vcc_hi, v252, 39
	v_lshl_add_u32 v154, s34, 8, v141
	v_ashrrev_i32_e32 v155, 31, v154
	s_nop 0
	v_lshl_add_u64 v[158:159], v[154:155], 2, vcc
	global_load_dword v144, v[158:159], off
	global_load_dword v148, v[158:159], off offset:64
	global_load_dword v152, v[158:159], off offset:128
	global_load_dword v183, v[158:159], off offset:192
	global_load_dword v230, v[158:159], off offset:512
	global_load_dword v231, v[158:159], off offset:576
	global_load_dword v233, v[158:159], off offset:640
	global_load_dword v250, v[158:159], off offset:704
	v_mov_b32_e32 v1, v0
	v_mov_b32_e32 v2, v0
	v_mov_b32_e32 v3, v0
	v_mov_b32_e32 v4, v0
	v_mov_b32_e32 v5, v0
	v_mov_b32_e32 v6, v0
	v_mov_b32_e32 v7, v0
	v_mov_b32_e32 v8, v0
	v_mov_b32_e32 v9, v0
	v_mov_b32_e32 v10, v0
	v_mov_b32_e32 v11, v0
	v_mov_b32_e32 v18, v0
	v_mov_b32_e32 v19, v0
	v_mov_b32_e32 v20, v0
	v_mov_b32_e32 v21, v0
	v_mov_b32_e32 v26, v0
	v_mov_b32_e32 v27, v0
	v_mov_b32_e32 v28, v0
	v_mov_b32_e32 v29, v0
	v_mov_b32_e32 v34, v0
	v_mov_b32_e32 v35, v0
	v_mov_b32_e32 v36, v0
	v_mov_b32_e32 v37, v0
	v_mov_b32_e32 v42, v0
	v_mov_b32_e32 v43, v0
	v_mov_b32_e32 v44, v0
	v_mov_b32_e32 v45, v0
	v_mov_b32_e32 v50, v0
	v_mov_b32_e32 v51, v0
	v_mov_b32_e32 v52, v0
	v_mov_b32_e32 v53, v0
	v_mov_b32_e32 v12, v0
	v_mov_b32_e32 v13, v0
	v_mov_b32_e32 v14, v0
	v_mov_b32_e32 v15, v0
	v_mov_b32_e32 v22, v0
	v_mov_b32_e32 v23, v0
	v_mov_b32_e32 v24, v0
	v_mov_b32_e32 v25, v0
	v_mov_b32_e32 v30, v0
	v_mov_b32_e32 v31, v0
	v_mov_b32_e32 v32, v0
	v_mov_b32_e32 v33, v0
	v_mov_b32_e32 v38, v0
	v_mov_b32_e32 v39, v0
	v_mov_b32_e32 v40, v0
	v_mov_b32_e32 v41, v0
	v_mov_b32_e32 v46, v0
	v_mov_b32_e32 v47, v0
	v_mov_b32_e32 v48, v0
	v_mov_b32_e32 v49, v0
	v_mov_b32_e32 v54, v0
	v_mov_b32_e32 v55, v0
	v_mov_b32_e32 v56, v0
	v_mov_b32_e32 v57, v0
	v_mov_b32_e32 v58, v0
	v_mov_b32_e32 v59, v0
	v_mov_b32_e32 v60, v0
	v_mov_b32_e32 v61, v0
	v_mov_b32_e32 v62, v0
	v_mov_b32_e32 v63, v0
	v_mov_b32_e32 v64, v0
	v_mov_b32_e32 v65, v0
	v_mov_b32_e32 v66, v0
	v_mov_b32_e32 v67, v0
	v_mov_b32_e32 v68, v0
	v_mov_b32_e32 v69, v0
	v_mov_b32_e32 v70, v0
	v_mov_b32_e32 v71, v0
	v_mov_b32_e32 v72, v0
	v_mov_b32_e32 v73, v0
	v_mov_b32_e32 v74, v0
	v_mov_b32_e32 v75, v0
	v_mov_b32_e32 v76, v0
	v_mov_b32_e32 v77, v0
	v_mov_b32_e32 v82, v0
	v_mov_b32_e32 v83, v0
	v_mov_b32_e32 v84, v0
	v_mov_b32_e32 v85, v0
	v_mov_b32_e32 v90, v0
	v_mov_b32_e32 v91, v0
	v_mov_b32_e32 v92, v0
	v_mov_b32_e32 v93, v0
	v_mov_b32_e32 v98, v0
	v_mov_b32_e32 v99, v0
	v_mov_b32_e32 v100, v0
	v_mov_b32_e32 v101, v0
	v_mov_b32_e32 v106, v0
	v_mov_b32_e32 v107, v0
	v_mov_b32_e32 v108, v0
	v_mov_b32_e32 v109, v0
	v_mov_b32_e32 v114, v0
	v_mov_b32_e32 v115, v0
	v_mov_b32_e32 v116, v0
	v_mov_b32_e32 v117, v0
	v_mov_b32_e32 v78, v0
	v_mov_b32_e32 v79, v0
	v_mov_b32_e32 v80, v0
	v_mov_b32_e32 v81, v0
	v_mov_b32_e32 v86, v0
	v_mov_b32_e32 v87, v0
	v_mov_b32_e32 v88, v0
	v_mov_b32_e32 v89, v0
	v_mov_b32_e32 v94, v0
	v_mov_b32_e32 v95, v0
	v_mov_b32_e32 v96, v0
	v_mov_b32_e32 v97, v0
	v_mov_b32_e32 v102, v0
	v_mov_b32_e32 v103, v0
	v_mov_b32_e32 v104, v0
	v_mov_b32_e32 v105, v0
	v_mov_b32_e32 v110, v0
	v_mov_b32_e32 v111, v0
	v_mov_b32_e32 v112, v0
	v_mov_b32_e32 v113, v0
	v_mov_b32_e32 v118, v0
	v_mov_b32_e32 v119, v0
	v_mov_b32_e32 v120, v0
	v_mov_b32_e32 v121, v0
	v_mov_b32_e32 v122, v0
	v_mov_b32_e32 v123, v0
	v_mov_b32_e32 v124, v0
	v_mov_b32_e32 v125, v0
	v_mov_b32_e32 v126, v0
	v_mov_b32_e32 v127, v0
	v_mov_b32_e32 v128, v0
	v_mov_b32_e32 v129, v0
.LBB0_670:
	s_add_u32 s40, s38, 0xfffc0080
	s_addc_u32 s41, s39, -1
	s_add_i32 s54, 0, 0x10000
	v_add_u32_e32 v140, s54, v145
	ds_read_b128 v[154:157], v140
	ds_read_b128 v[158:161], v140 offset:1024
	ds_read_b128 v[162:165], v140 offset:2048
	ds_read_b128 v[166:169], v140 offset:3072
	s_cmp_eq_u32 s53, 12
	s_cselect_b32 s43, s11, s41
	s_cselect_b32 s42, s17, s40
	s_cselect_b32 s41, s23, s52
	s_cselect_b32 s40, s44, s45
	v_lshl_add_u64 v[142:143], s[38:39], 0, v[136:137]
	s_add_i32 m0, s21, 0xc000
	ds_read_b128 v[170:173], v153
	ds_read_b128 v[174:177], v153 offset:1024
	ds_read_b128 v[188:191], v153 offset:2048
	ds_read_b128 v[192:195], v153 offset:3072
	ds_read_b128 v[196:199], v153 offset:4096
	ds_read_b128 v[200:203], v153 offset:5120
	ds_read_b128 v[204:207], v153 offset:6144
	ds_read_b128 v[208:211], v153 offset:7168
	global_load_lds_dwordx4 v[142:143], off
	v_lshl_add_u64 v[142:143], s[38:39], 0, v[138:139]
	s_add_i32 m0, s21, 0xe000
	s_nop 0
	global_load_lds_dwordx4 v[142:143], off
	s_waitcnt lgkmcnt(8)
	s_barrier
	s_waitcnt lgkmcnt(0)
	s_setprio 1
	s_waitcnt lgkmcnt(0)
	v_mfma_f32_16x16x32_bf16 v[126:129], v[154:157], v[170:173], v[126:129]
	v_mfma_f32_16x16x32_bf16 v[122:125], v[162:165], v[170:173], v[122:125]
	v_mfma_f32_16x16x32_bf16 v[118:121], v[154:157], v[188:191], v[118:121]
	v_mfma_f32_16x16x32_bf16 v[110:113], v[162:165], v[188:191], v[110:113]
	v_mfma_f32_16x16x32_bf16 v[102:105], v[154:157], v[196:199], v[102:105]
	v_mfma_f32_16x16x32_bf16 v[94:97], v[162:165], v[196:199], v[94:97]
	v_mfma_f32_16x16x32_bf16 v[86:89], v[154:157], v[204:207], v[86:89]
	v_mfma_f32_16x16x32_bf16 v[78:81], v[162:165], v[204:207], v[78:81]
	v_mfma_f32_16x16x32_bf16 v[126:129], v[158:161], v[174:177], v[126:129]
	v_mfma_f32_16x16x32_bf16 v[122:125], v[166:169], v[174:177], v[122:125]
	v_mfma_f32_16x16x32_bf16 v[118:121], v[158:161], v[192:195], v[118:121]
	v_mfma_f32_16x16x32_bf16 v[110:113], v[166:169], v[192:195], v[110:113]
	v_mfma_f32_16x16x32_bf16 v[102:105], v[158:161], v[200:203], v[102:105]
	v_mfma_f32_16x16x32_bf16 v[94:97], v[166:169], v[200:203], v[94:97]
	v_mfma_f32_16x16x32_bf16 v[86:89], v[158:161], v[208:211], v[86:89]
	v_mfma_f32_16x16x32_bf16 v[78:81], v[166:169], v[208:211], v[78:81]
	s_setprio 0
	s_barrier
	s_add_i32 s56, 0, 0x14000
	s_add_i32 s54, s54, s20
	v_add_u32_e32 v140, s56, v145
	v_lshl_add_u64 v[142:143], s[40:41], 0, v[16:17]
	s_mov_b32 m0, s54
	ds_read_b128 v[212:215], v140
	ds_read_b128 v[216:219], v140 offset:1024
	ds_read_b128 v[220:223], v140 offset:2048
	ds_read_b128 v[224:227], v140 offset:3072
	global_load_lds_dwordx4 v[142:143], off
	v_lshl_add_u64 v[146:147], s[40:41], 0, v[134:135]
	s_add_i32 m0, s54, 0x2000
	s_nop 0
	global_load_lds_dwordx4 v[146:147], off
	s_barrier
	s_waitcnt lgkmcnt(0)
	s_setprio 1
	s_waitcnt lgkmcnt(0)
	v_mfma_f32_16x16x32_bf16 v[114:117], v[212:215], v[170:173], v[114:117]
	v_mfma_f32_16x16x32_bf16 v[106:109], v[220:223], v[170:173], v[106:109]
	v_mfma_f32_16x16x32_bf16 v[98:101], v[212:215], v[188:191], v[98:101]
	v_mfma_f32_16x16x32_bf16 v[90:93], v[220:223], v[188:191], v[90:93]
	v_mfma_f32_16x16x32_bf16 v[82:85], v[212:215], v[196:199], v[82:85]
	v_mfma_f32_16x16x32_bf16 v[74:77], v[220:223], v[196:199], v[74:77]
	v_mfma_f32_16x16x32_bf16 v[70:73], v[212:215], v[204:207], v[70:73]
	v_mfma_f32_16x16x32_bf16 v[66:69], v[220:223], v[204:207], v[66:69]
	v_mfma_f32_16x16x32_bf16 v[114:117], v[216:219], v[174:177], v[114:117]
	v_mfma_f32_16x16x32_bf16 v[106:109], v[224:227], v[174:177], v[106:109]
	v_mfma_f32_16x16x32_bf16 v[98:101], v[216:219], v[192:195], v[98:101]
	v_mfma_f32_16x16x32_bf16 v[90:93], v[224:227], v[192:195], v[90:93]
	v_mfma_f32_16x16x32_bf16 v[82:85], v[216:219], v[200:203], v[82:85]
	v_mfma_f32_16x16x32_bf16 v[74:77], v[224:227], v[200:203], v[74:77]
	v_mfma_f32_16x16x32_bf16 v[70:73], v[216:219], v[208:211], v[70:73]
	v_mfma_f32_16x16x32_bf16 v[66:69], v[224:227], v[208:211], v[66:69]
	s_setprio 0
	s_mov_b32 m0, s21
	v_lshl_add_u64 v[150:151], s[42:43], 0, v[130:131]
	s_barrier
	ds_read_b128 v[170:173], v153 offset:16384
	ds_read_b128 v[174:177], v153 offset:17408
	ds_read_b128 v[188:191], v153 offset:18432
	ds_read_b128 v[192:195], v153 offset:19456
	ds_read_b128 v[196:199], v153 offset:20480
	ds_read_b128 v[200:203], v153 offset:21504
	ds_read_b128 v[204:207], v153 offset:22528
	ds_read_b128 v[208:211], v153 offset:23552
	global_load_lds_dwordx4 v[150:151], off
	v_lshl_add_u64 v[178:179], s[42:43], 0, v[132:133]
	s_mov_b32 m0, s25
	s_nop 0
	global_load_lds_dwordx4 v[178:179], off
	s_barrier
	s_waitcnt lgkmcnt(0)
	s_setprio 1
	s_waitcnt lgkmcnt(0)
	v_mfma_f32_16x16x32_bf16 v[62:65], v[154:157], v[170:173], v[62:65]
	v_mfma_f32_16x16x32_bf16 v[58:61], v[162:165], v[170:173], v[58:61]
	v_mfma_f32_16x16x32_bf16 v[54:57], v[154:157], v[188:191], v[54:57]
	v_mfma_f32_16x16x32_bf16 v[46:49], v[162:165], v[188:191], v[46:49]
	v_mfma_f32_16x16x32_bf16 v[38:41], v[154:157], v[196:199], v[38:41]
	v_mfma_f32_16x16x32_bf16 v[30:33], v[162:165], v[196:199], v[30:33]
	v_mfma_f32_16x16x32_bf16 v[22:25], v[154:157], v[204:207], v[22:25]
	v_mfma_f32_16x16x32_bf16 v[12:15], v[162:165], v[204:207], v[12:15]
	v_mfma_f32_16x16x32_bf16 v[62:65], v[158:161], v[174:177], v[62:65]
	v_mfma_f32_16x16x32_bf16 v[58:61], v[166:169], v[174:177], v[58:61]
	v_mfma_f32_16x16x32_bf16 v[54:57], v[158:161], v[192:195], v[54:57]
	v_mfma_f32_16x16x32_bf16 v[46:49], v[166:169], v[192:195], v[46:49]
	v_mfma_f32_16x16x32_bf16 v[38:41], v[158:161], v[200:203], v[38:41]
	v_mfma_f32_16x16x32_bf16 v[30:33], v[166:169], v[200:203], v[30:33]
	v_mfma_f32_16x16x32_bf16 v[22:25], v[158:161], v[208:211], v[22:25]
	v_mfma_f32_16x16x32_bf16 v[12:15], v[166:169], v[208:211], v[12:15]
	s_setprio 0
	s_barrier
	s_add_u32 s54, s40, 0x40000
	s_addc_u32 s55, s41, 0
	s_add_i32 s56, s56, s20
	v_lshl_add_u64 v[154:155], s[54:55], 0, v[16:17]
	s_mov_b32 m0, s56
	s_nop 0
	global_load_lds_dwordx4 v[154:155], off
	v_lshl_add_u64 v[154:155], s[54:55], 0, v[134:135]
	s_add_i32 m0, s56, 0x2000
	s_nop 0
	global_load_lds_dwordx4 v[154:155], off
	s_waitcnt vmcnt(6)
	s_barrier
	s_setprio 1
	v_mfma_f32_16x16x32_bf16 v[50:53], v[212:215], v[170:173], v[50:53]
	v_mfma_f32_16x16x32_bf16 v[42:45], v[220:223], v[170:173], v[42:45]
	v_mfma_f32_16x16x32_bf16 v[34:37], v[212:215], v[188:191], v[34:37]
	v_mfma_f32_16x16x32_bf16 v[26:29], v[220:223], v[188:191], v[26:29]
	v_mfma_f32_16x16x32_bf16 v[18:21], v[212:215], v[196:199], v[18:21]
	v_mfma_f32_16x16x32_bf16 v[8:11], v[220:223], v[196:199], v[8:11]
	v_mfma_f32_16x16x32_bf16 v[4:7], v[212:215], v[204:207], v[4:7]
	v_mfma_f32_16x16x32_bf16 v[0:3], v[220:223], v[204:207], v[0:3]
	v_mfma_f32_16x16x32_bf16 v[50:53], v[216:219], v[174:177], v[50:53]
	v_mfma_f32_16x16x32_bf16 v[42:45], v[224:227], v[174:177], v[42:45]
	v_mfma_f32_16x16x32_bf16 v[34:37], v[216:219], v[192:195], v[34:37]
	v_mfma_f32_16x16x32_bf16 v[26:29], v[224:227], v[192:195], v[26:29]
	v_mfma_f32_16x16x32_bf16 v[18:21], v[216:219], v[200:203], v[18:21]
	v_mfma_f32_16x16x32_bf16 v[8:11], v[224:227], v[200:203], v[8:11]
	v_mfma_f32_16x16x32_bf16 v[4:7], v[216:219], v[208:211], v[4:7]
	v_mfma_f32_16x16x32_bf16 v[0:3], v[224:227], v[208:211], v[0:3]
	s_setprio 0
	s_add_i32 s54, 0, 0x18000
	v_add_u32_e32 v140, s54, v145
	s_barrier
	ds_read_b128 v[154:157], v140
	ds_read_b128 v[158:161], v140 offset:1024
	ds_read_b128 v[162:165], v140 offset:2048
	ds_read_b128 v[166:169], v140 offset:3072
	s_add_u32 s42, s42, 0x40000
	s_addc_u32 s43, s43, 0
	s_mov_b32 m0, s33
	v_lshl_add_u64 v[180:181], s[42:43], 0, v[130:131]
	ds_read_b128 v[170:173], v153 offset:32768
	ds_read_b128 v[174:177], v153 offset:33792
	ds_read_b128 v[188:191], v153 offset:34816
	ds_read_b128 v[192:195], v153 offset:35840
	ds_read_b128 v[196:199], v153 offset:36864
	ds_read_b128 v[200:203], v153 offset:37888
	ds_read_b128 v[204:207], v153 offset:38912
	ds_read_b128 v[208:211], v153 offset:39936
	global_load_lds_dwordx4 v[180:181], off
	v_lshl_add_u64 v[180:181], s[42:43], 0, v[132:133]
	s_mov_b32 m0, s35
	s_nop 0
	global_load_lds_dwordx4 v[180:181], off
	s_waitcnt lgkmcnt(8)
	s_barrier
	s_waitcnt lgkmcnt(0)
	s_setprio 1
	s_waitcnt lgkmcnt(0)
	v_mfma_f32_16x16x32_bf16 v[126:129], v[154:157], v[170:173], v[126:129]
	v_mfma_f32_16x16x32_bf16 v[122:125], v[162:165], v[170:173], v[122:125]
	v_mfma_f32_16x16x32_bf16 v[118:121], v[154:157], v[188:191], v[118:121]
	v_mfma_f32_16x16x32_bf16 v[110:113], v[162:165], v[188:191], v[110:113]
	v_mfma_f32_16x16x32_bf16 v[102:105], v[154:157], v[196:199], v[102:105]
	v_mfma_f32_16x16x32_bf16 v[94:97], v[162:165], v[196:199], v[94:97]
	v_mfma_f32_16x16x32_bf16 v[86:89], v[154:157], v[204:207], v[86:89]
	v_mfma_f32_16x16x32_bf16 v[78:81], v[162:165], v[204:207], v[78:81]
	v_mfma_f32_16x16x32_bf16 v[126:129], v[158:161], v[174:177], v[126:129]
	v_mfma_f32_16x16x32_bf16 v[122:125], v[166:169], v[174:177], v[122:125]
	v_mfma_f32_16x16x32_bf16 v[118:121], v[158:161], v[192:195], v[118:121]
	v_mfma_f32_16x16x32_bf16 v[110:113], v[166:169], v[192:195], v[110:113]
	v_mfma_f32_16x16x32_bf16 v[102:105], v[158:161], v[200:203], v[102:105]
	v_mfma_f32_16x16x32_bf16 v[94:97], v[166:169], v[200:203], v[94:97]
	v_mfma_f32_16x16x32_bf16 v[86:89], v[158:161], v[208:211], v[86:89]
	v_mfma_f32_16x16x32_bf16 v[78:81], v[166:169], v[208:211], v[78:81]
	s_setprio 0
	s_barrier
	s_add_i32 s42, 0, 0x1c000
	s_add_i32 s43, s54, s20
	v_add_u32_e32 v140, s42, v145
	v_lshl_add_u64 v[142:143], v[142:143], 0, s[14:15]
	s_mov_b32 m0, s43
	ds_read_b128 v[212:215], v140
	ds_read_b128 v[216:219], v140 offset:1024
	ds_read_b128 v[220:223], v140 offset:2048
	ds_read_b128 v[224:227], v140 offset:3072
	global_load_lds_dwordx4 v[142:143], off
	v_lshl_add_u64 v[142:143], v[146:147], 0, s[14:15]
	s_add_i32 m0, s43, 0x2000
	s_nop 0
	global_load_lds_dwordx4 v[142:143], off
	s_barrier
	s_waitcnt lgkmcnt(0)
	s_setprio 1
	s_waitcnt lgkmcnt(0)
	v_mfma_f32_16x16x32_bf16 v[114:117], v[212:215], v[170:173], v[114:117]
	v_mfma_f32_16x16x32_bf16 v[106:109], v[220:223], v[170:173], v[106:109]
	v_mfma_f32_16x16x32_bf16 v[98:101], v[212:215], v[188:191], v[98:101]
	v_mfma_f32_16x16x32_bf16 v[90:93], v[220:223], v[188:191], v[90:93]
	v_mfma_f32_16x16x32_bf16 v[82:85], v[212:215], v[196:199], v[82:85]
	v_mfma_f32_16x16x32_bf16 v[74:77], v[220:223], v[196:199], v[74:77]
	v_mfma_f32_16x16x32_bf16 v[70:73], v[212:215], v[204:207], v[70:73]
	v_mfma_f32_16x16x32_bf16 v[66:69], v[220:223], v[204:207], v[66:69]
	v_mfma_f32_16x16x32_bf16 v[114:117], v[216:219], v[174:177], v[114:117]
	v_mfma_f32_16x16x32_bf16 v[106:109], v[224:227], v[174:177], v[106:109]
	v_mfma_f32_16x16x32_bf16 v[98:101], v[216:219], v[192:195], v[98:101]
	v_mfma_f32_16x16x32_bf16 v[90:93], v[224:227], v[192:195], v[90:93]
	v_mfma_f32_16x16x32_bf16 v[82:85], v[216:219], v[200:203], v[82:85]
	v_mfma_f32_16x16x32_bf16 v[74:77], v[224:227], v[200:203], v[74:77]
	v_mfma_f32_16x16x32_bf16 v[70:73], v[216:219], v[208:211], v[70:73]
	v_mfma_f32_16x16x32_bf16 v[66:69], v[224:227], v[208:211], v[66:69]
	s_setprio 0
	s_mov_b32 m0, s46
	v_lshl_add_u64 v[142:143], v[150:151], 0, s[14:15]
	s_barrier
	ds_read_b128 v[170:173], v153 offset:49152
	ds_read_b128 v[174:177], v153 offset:50176
	ds_read_b128 v[188:191], v153 offset:51200
	ds_read_b128 v[192:195], v153 offset:52224
	ds_read_b128 v[196:199], v153 offset:53248
	ds_read_b128 v[200:203], v153 offset:54272
	ds_read_b128 v[204:207], v153 offset:55296
	ds_read_b128 v[208:211], v153 offset:56320
	global_load_lds_dwordx4 v[142:143], off
	v_lshl_add_u64 v[142:143], v[178:179], 0, s[14:15]
	s_mov_b32 m0, s47
	s_nop 0
	global_load_lds_dwordx4 v[142:143], off
	s_barrier
	s_waitcnt lgkmcnt(0)
	s_setprio 1
	s_waitcnt lgkmcnt(0)
	v_mfma_f32_16x16x32_bf16 v[62:65], v[154:157], v[170:173], v[62:65]
	v_mfma_f32_16x16x32_bf16 v[58:61], v[162:165], v[170:173], v[58:61]
	v_mfma_f32_16x16x32_bf16 v[54:57], v[154:157], v[188:191], v[54:57]
	v_mfma_f32_16x16x32_bf16 v[46:49], v[162:165], v[188:191], v[46:49]
	v_mfma_f32_16x16x32_bf16 v[38:41], v[154:157], v[196:199], v[38:41]
	v_mfma_f32_16x16x32_bf16 v[30:33], v[162:165], v[196:199], v[30:33]
	v_mfma_f32_16x16x32_bf16 v[22:25], v[154:157], v[204:207], v[22:25]
	v_mfma_f32_16x16x32_bf16 v[12:15], v[162:165], v[204:207], v[12:15]
	v_mfma_f32_16x16x32_bf16 v[62:65], v[158:161], v[174:177], v[62:65]
	v_mfma_f32_16x16x32_bf16 v[58:61], v[166:169], v[174:177], v[58:61]
	v_mfma_f32_16x16x32_bf16 v[54:57], v[158:161], v[192:195], v[54:57]
	v_mfma_f32_16x16x32_bf16 v[46:49], v[166:169], v[192:195], v[46:49]
	v_mfma_f32_16x16x32_bf16 v[38:41], v[158:161], v[200:203], v[38:41]
	v_mfma_f32_16x16x32_bf16 v[30:33], v[166:169], v[200:203], v[30:33]
	v_mfma_f32_16x16x32_bf16 v[22:25], v[158:161], v[208:211], v[22:25]
	v_mfma_f32_16x16x32_bf16 v[12:15], v[166:169], v[208:211], v[12:15]
	s_setprio 0
	s_barrier
	s_add_u32 s40, s40, 0x40080
	s_addc_u32 s41, s41, 0
	s_add_i32 s42, s42, s20
	v_lshl_add_u64 v[142:143], s[40:41], 0, v[16:17]
	s_mov_b32 m0, s42
	s_nop 0
	global_load_lds_dwordx4 v[142:143], off
	v_lshl_add_u64 v[142:143], s[40:41], 0, v[134:135]
	s_add_i32 m0, s42, 0x2000
	s_nop 0
	global_load_lds_dwordx4 v[142:143], off
	s_waitcnt vmcnt(6)
	s_barrier
	s_setprio 1
	v_mfma_f32_16x16x32_bf16 v[50:53], v[212:215], v[170:173], v[50:53]
	v_mfma_f32_16x16x32_bf16 v[42:45], v[220:223], v[170:173], v[42:45]
	v_mfma_f32_16x16x32_bf16 v[34:37], v[212:215], v[188:191], v[34:37]
	v_mfma_f32_16x16x32_bf16 v[26:29], v[220:223], v[188:191], v[26:29]
	v_mfma_f32_16x16x32_bf16 v[18:21], v[212:215], v[196:199], v[18:21]
	v_mfma_f32_16x16x32_bf16 v[8:11], v[220:223], v[196:199], v[8:11]
	v_mfma_f32_16x16x32_bf16 v[4:7], v[212:215], v[204:207], v[4:7]
	v_mfma_f32_16x16x32_bf16 v[0:3], v[220:223], v[204:207], v[0:3]
	v_mfma_f32_16x16x32_bf16 v[50:53], v[216:219], v[174:177], v[50:53]
	v_mfma_f32_16x16x32_bf16 v[42:45], v[224:227], v[174:177], v[42:45]
	v_mfma_f32_16x16x32_bf16 v[34:37], v[216:219], v[192:195], v[34:37]
	v_mfma_f32_16x16x32_bf16 v[26:29], v[224:227], v[192:195], v[26:29]
	v_mfma_f32_16x16x32_bf16 v[18:21], v[216:219], v[200:203], v[18:21]
	v_mfma_f32_16x16x32_bf16 v[8:11], v[224:227], v[200:203], v[8:11]
	v_mfma_f32_16x16x32_bf16 v[4:7], v[216:219], v[208:211], v[4:7]
	v_mfma_f32_16x16x32_bf16 v[0:3], v[224:227], v[208:211], v[0:3]
	s_setprio 0
	s_add_i32 s53, s53, 2
	s_add_u32 s38, s38, 0x100
	s_addc_u32 s39, s39, 0
	s_add_u32 s45, s45, 0x100
	s_addc_u32 s52, s52, 0
	s_cmp_gt_u32 s53, 13
	s_barrier
	s_cbranch_scc0 .LBB0_670
	v_lshl_add_u32 v168, s34, 8, v141
	v_readlane_b32 s38, v252, 38
	v_ashrrev_i32_e32 v169, 31, v168
	v_or_b32_e32 v164, 16, v168
	v_or_b32_e32 v160, 32, v168
	v_or_b32_e32 v154, 48, v168
	v_readlane_b32 s39, v252, 39
	v_ashrrev_i32_e32 v165, 31, v164
	v_ashrrev_i32_e32 v161, 31, v160
	v_ashrrev_i32_e32 v155, 31, v154
	v_lshl_add_u64 v[142:143], v[168:169], 2, s[38:39]
	v_lshl_add_u64 v[146:147], v[164:165], 2, s[38:39]
	v_lshl_add_u64 v[150:151], v[160:161], 2, s[38:39]
	v_lshl_add_u64 v[156:157], v[154:155], 2, s[38:39]
	s_waitcnt vmcnt(6)
	v_mov_b32_e32 v170, v144
	v_mov_b32_e32 v166, v148
	v_mov_b32_e32 v162, v152
	v_mov_b32_e32 v158, v183
	v_mov_b32_e32 v152, v230
	v_mov_b32_e32 v148, v231
	v_mov_b32_e32 v144, v233
	v_mov_b32_e32 v140, v250
	v_add_u32_e32 v156, 0x80, v168
	v_add_u32_e32 v150, 0x90, v168
	v_add_u32_e32 v146, 0xa0, v168
	v_add_u32_e32 v142, 0xb0, v168
	v_lshl_or_b32 v172, s22, 8, v149
	s_cmp_eq_u32 s51, 0
	v_ashrrev_i32_e32 v157, 31, v156
	v_ashrrev_i32_e32 v151, 31, v150
	v_ashrrev_i32_e32 v147, 31, v146
	v_ashrrev_i32_e32 v143, 31, v142
	v_ashrrev_i32_e32 v173, 31, v172
	s_cbranch_scc1 .LBB0_673
	v_mul_f32_e32 v176, v124, v170
	v_mul_f32_e32 v176, 0xbfb8aa3b, v176
	v_exp_f32_e32 v176, v176
	v_mul_f32_e32 v159, v126, v170
	v_mul_f32_e32 v167, v127, v170
	v_lshlrev_b64 v[174:175], 12, v[168:169]
	v_mul_f32_e32 v159, 0xbfb8aa3b, v159
	v_mul_f32_e32 v163, v122, v170
	v_mul_f32_e32 v167, 0xbfb8aa3b, v167
	v_mul_f32_e32 v169, v123, v170
	v_mul_f32_e32 v171, v128, v170
	v_add_f32_e32 v176, 1.0, v176
	v_mul_f32_e32 v177, v129, v170
	v_exp_f32_e32 v159, v159
	v_mul_f32_e32 v163, 0xbfb8aa3b, v163
	v_exp_f32_e32 v167, v167
	v_mul_f32_e32 v169, 0xbfb8aa3b, v169
	v_mul_f32_e32 v171, 0xbfb8aa3b, v171
	v_rcp_f32_e32 v176, v176
	v_mul_f32_e32 v177, 0xbfb8aa3b, v177
	v_mul_f32_e32 v178, v125, v170
	v_exp_f32_e32 v163, v163
	v_exp_f32_e32 v169, v169
	v_exp_f32_e32 v171, v171
	v_exp_f32_e32 v177, v177
	v_mul_f32_e32 v178, 0xbfb8aa3b, v178
	v_exp_f32_e32 v178, v178
	v_add_f32_e32 v159, 1.0, v159
	v_add_f32_e32 v167, 1.0, v167
	v_fma_f32 v176, v176, s31, 0.5
	v_rcp_f32_e32 v159, v159
	v_add_f32_e32 v163, 1.0, v163
	v_rcp_f32_e32 v167, v167
	v_add_f32_e32 v169, 1.0, v169
	v_add_f32_e32 v171, 1.0, v171
	v_max_f32_e32 v176, 1.0, v176
	v_add_f32_e32 v177, 1.0, v177
	v_rcp_f32_e32 v163, v163
	v_rcp_f32_e32 v169, v169
	v_rcp_f32_e32 v171, v171
	v_rcp_f32_e32 v177, v177
	v_cvt_u32_f32_sdwa v179, v176 dst_sel:WORD_1 dst_unused:UNUSED_PAD src0_sel:DWORD
	v_add_f32_e32 v176, 1.0, v178
	v_rcp_f32_e32 v176, v176
	v_fma_f32 v159, v159, s31, 0.5
	v_fma_f32 v167, v167, s31, 0.5
	v_max_f32_e32 v159, 1.0, v159
	v_fma_f32 v163, v163, s31, 0.5
	v_max_f32_e32 v167, 1.0, v167
	v_fma_f32 v169, v169, s31, 0.5
	v_fma_f32 v171, v171, s31, 0.5
	v_fma_f32 v177, v177, s31, 0.5
	v_cvt_u32_f32_e32 v159, v159
	v_max_f32_e32 v163, 1.0, v163
	v_cvt_u32_f32_e32 v167, v167
	v_max_f32_e32 v169, 1.0, v169
	v_max_f32_e32 v171, 1.0, v171
	v_max_f32_e32 v177, 1.0, v177
	v_fma_f32 v176, v176, s31, 0.5
	v_cvt_u32_f32_e32 v163, v163
	v_cvt_u32_f32_e32 v169, v169
	v_cvt_u32_f32_sdwa v171, v171 dst_sel:WORD_1 dst_unused:UNUSED_PAD src0_sel:DWORD
	v_cvt_u32_f32_sdwa v177, v177 dst_sel:BYTE_3 dst_unused:UNUSED_PAD src0_sel:DWORD
	v_max_f32_e32 v176, 1.0, v176
	v_cvt_u32_f32_sdwa v178, v176 dst_sel:BYTE_3 dst_unused:UNUSED_PAD src0_sel:DWORD
	v_readlane_b32 s22, v252, 34
	v_readlane_b32 s23, v252, 35
	v_lshl_or_b32 v159, v167, 8, v159
	v_or3_b32 v176, v159, v171, v177
	v_lshl_add_u64 v[174:175], s[22:23], 0, v[174:175]
	v_lshl_or_b32 v159, v169, 8, v163
	v_lshl_add_u64 v[174:175], v[174:175], 0, v[172:173]
	v_or3_b32 v177, v159, v179, v178
	global_store_dwordx2 v[174:175], v[176:177], off
	v_mul_f32_e32 v176, v108, v170
	v_mul_f32_e32 v176, 0xbfb8aa3b, v176
	v_exp_f32_e32 v176, v176
	v_mul_f32_e32 v159, v114, v170
	v_mul_f32_e32 v167, v115, v170
	v_mul_f32_e32 v159, 0xbfb8aa3b, v159
	v_mul_f32_e32 v163, v106, v170
	v_mul_f32_e32 v167, 0xbfb8aa3b, v167
	v_mul_f32_e32 v169, v107, v170
	v_mul_f32_e32 v171, v116, v170
	v_add_f32_e32 v176, 1.0, v176
	v_mul_f32_e32 v177, v117, v170
	v_exp_f32_e32 v159, v159
	v_mul_f32_e32 v163, 0xbfb8aa3b, v163
	v_exp_f32_e32 v167, v167
	v_mul_f32_e32 v169, 0xbfb8aa3b, v169
	v_mul_f32_e32 v171, 0xbfb8aa3b, v171
	v_rcp_f32_e32 v176, v176
	v_mul_f32_e32 v177, 0xbfb8aa3b, v177
	v_mul_f32_e32 v178, v109, v170
	v_exp_f32_e32 v163, v163
	v_exp_f32_e32 v169, v169
	v_exp_f32_e32 v171, v171
	v_exp_f32_e32 v177, v177
	v_mul_f32_e32 v178, 0xbfb8aa3b, v178
	v_exp_f32_e32 v178, v178
	v_add_f32_e32 v159, 1.0, v159
	v_add_f32_e32 v167, 1.0, v167
	v_fma_f32 v176, v176, s31, 0.5
	v_rcp_f32_e32 v159, v159
	v_add_f32_e32 v163, 1.0, v163
	v_rcp_f32_e32 v167, v167
	v_add_f32_e32 v169, 1.0, v169
	v_add_f32_e32 v171, 1.0, v171
	v_max_f32_e32 v176, 1.0, v176
	v_add_f32_e32 v177, 1.0, v177
	v_rcp_f32_e32 v163, v163
	v_rcp_f32_e32 v169, v169
	v_rcp_f32_e32 v171, v171
	v_rcp_f32_e32 v177, v177
	v_cvt_u32_f32_sdwa v179, v176 dst_sel:WORD_1 dst_unused:UNUSED_PAD src0_sel:DWORD
	v_add_f32_e32 v176, 1.0, v178
	v_rcp_f32_e32 v176, v176
	v_fma_f32 v159, v159, s31, 0.5
	v_fma_f32 v167, v167, s31, 0.5
	v_max_f32_e32 v159, 1.0, v159
	v_fma_f32 v163, v163, s31, 0.5
	v_max_f32_e32 v167, 1.0, v167
	v_fma_f32 v169, v169, s31, 0.5
	v_fma_f32 v171, v171, s31, 0.5
	v_fma_f32 v177, v177, s31, 0.5
	v_cvt_u32_f32_e32 v159, v159
	v_max_f32_e32 v163, 1.0, v163
	v_cvt_u32_f32_e32 v167, v167
	v_max_f32_e32 v169, 1.0, v169
	v_max_f32_e32 v171, 1.0, v171
	v_max_f32_e32 v177, 1.0, v177
	v_fma_f32 v176, v176, s31, 0.5
	v_cvt_u32_f32_e32 v163, v163
	v_cvt_u32_f32_e32 v169, v169
	v_cvt_u32_f32_sdwa v171, v171 dst_sel:WORD_1 dst_unused:UNUSED_PAD src0_sel:DWORD
	v_cvt_u32_f32_sdwa v177, v177 dst_sel:BYTE_3 dst_unused:UNUSED_PAD src0_sel:DWORD
	v_max_f32_e32 v176, 1.0, v176
	v_cvt_u32_f32_sdwa v178, v176 dst_sel:BYTE_3 dst_unused:UNUSED_PAD src0_sel:DWORD
	v_lshl_or_b32 v159, v167, 8, v159
	v_or3_b32 v176, v159, v171, v177
	v_lshl_or_b32 v159, v169, 8, v163
	v_or3_b32 v177, v159, v179, v178
	global_store_dwordx2 v[174:175], v[176:177], off offset:128
	v_lshlrev_b64 v[174:175], 12, v[164:165]
	v_mul_f32_e32 v159, v118, v166
	v_mul_f32_e32 v165, v119, v166
	v_mul_f32_e32 v159, 0xbfb8aa3b, v159
	v_mul_f32_e32 v163, v110, v166
	v_mul_f32_e32 v165, 0xbfb8aa3b, v165
	v_mul_f32_e32 v167, v111, v166
	v_mul_f32_e32 v169, v120, v166
	v_mul_f32_e32 v176, v121, v166
	v_exp_f32_e32 v159, v159
	v_mul_f32_e32 v163, 0xbfb8aa3b, v163
	v_exp_f32_e32 v165, v165
	v_mul_f32_e32 v167, 0xbfb8aa3b, v167
	v_mul_f32_e32 v169, 0xbfb8aa3b, v169
	v_mul_f32_e32 v171, v112, v166
	v_mul_f32_e32 v176, 0xbfb8aa3b, v176
	v_mul_f32_e32 v177, v113, v166
	v_exp_f32_e32 v163, v163
	v_exp_f32_e32 v167, v167
	v_exp_f32_e32 v169, v169
	v_mul_f32_e32 v171, 0xbfb8aa3b, v171
	v_exp_f32_e32 v176, v176
	v_mul_f32_e32 v177, 0xbfb8aa3b, v177
	v_exp_f32_e32 v171, v171
	v_exp_f32_e32 v177, v177
	v_add_f32_e32 v159, 1.0, v159
	v_add_f32_e32 v165, 1.0, v165
	v_rcp_f32_e32 v159, v159
	v_add_f32_e32 v163, 1.0, v163
	v_rcp_f32_e32 v165, v165
	v_add_f32_e32 v167, 1.0, v167
	v_add_f32_e32 v169, 1.0, v169
	v_add_f32_e32 v176, 1.0, v176
	v_rcp_f32_e32 v163, v163
	v_rcp_f32_e32 v167, v167
	v_rcp_f32_e32 v169, v169
	v_add_f32_e32 v171, 1.0, v171
	v_rcp_f32_e32 v176, v176
	v_add_f32_e32 v177, 1.0, v177
	v_rcp_f32_e32 v171, v171
	v_rcp_f32_e32 v177, v177
	v_fma_f32 v159, v159, s31, 0.5
	v_fma_f32 v165, v165, s31, 0.5
	v_max_f32_e32 v159, 1.0, v159
	v_fma_f32 v163, v163, s31, 0.5
	v_max_f32_e32 v165, 1.0, v165
	v_fma_f32 v167, v167, s31, 0.5
	v_fma_f32 v169, v169, s31, 0.5
	v_fma_f32 v176, v176, s31, 0.5
	v_cvt_u32_f32_e32 v159, v159
	v_max_f32_e32 v163, 1.0, v163
	v_cvt_u32_f32_e32 v165, v165
	v_max_f32_e32 v167, 1.0, v167
	v_max_f32_e32 v169, 1.0, v169
	v_fma_f32 v171, v171, s31, 0.5
	v_max_f32_e32 v176, 1.0, v176
	v_fma_f32 v177, v177, s31, 0.5
	v_cvt_u32_f32_e32 v163, v163
	v_cvt_u32_f32_e32 v167, v167
	v_cvt_u32_f32_sdwa v169, v169 dst_sel:WORD_1 dst_unused:UNUSED_PAD src0_sel:DWORD
	v_max_f32_e32 v171, 1.0, v171
	v_cvt_u32_f32_sdwa v176, v176 dst_sel:BYTE_3 dst_unused:UNUSED_PAD src0_sel:DWORD
	v_max_f32_e32 v177, 1.0, v177
	v_cvt_u32_f32_sdwa v171, v171 dst_sel:WORD_1 dst_unused:UNUSED_PAD src0_sel:DWORD
	v_cvt_u32_f32_sdwa v177, v177 dst_sel:BYTE_3 dst_unused:UNUSED_PAD src0_sel:DWORD
	v_lshl_or_b32 v159, v165, 8, v159
	v_lshl_add_u64 v[174:175], s[22:23], 0, v[174:175]
	v_or3_b32 v176, v159, v169, v176
	v_lshl_or_b32 v159, v167, 8, v163
	v_lshl_add_u64 v[174:175], v[174:175], 0, v[172:173]
	v_or3_b32 v177, v159, v171, v177
	v_mul_f32_e32 v159, v98, v166
	v_mul_f32_e32 v165, v99, v166
	v_mul_f32_e32 v159, 0xbfb8aa3b, v159
	v_mul_f32_e32 v163, v90, v166
	global_store_dwordx2 v[174:175], v[176:177], off
	v_mul_f32_e32 v165, 0xbfb8aa3b, v165
	v_mul_f32_e32 v167, v91, v166
	v_mul_f32_e32 v169, v100, v166
	v_mul_f32_e32 v176, v101, v166
	v_exp_f32_e32 v159, v159
	v_mul_f32_e32 v163, 0xbfb8aa3b, v163
	v_exp_f32_e32 v165, v165
	v_mul_f32_e32 v167, 0xbfb8aa3b, v167
	v_mul_f32_e32 v169, 0xbfb8aa3b, v169
	v_mul_f32_e32 v171, v92, v166
	v_mul_f32_e32 v176, 0xbfb8aa3b, v176
	v_mul_f32_e32 v177, v93, v166
	v_exp_f32_e32 v163, v163
	v_exp_f32_e32 v167, v167
	v_exp_f32_e32 v169, v169
	v_mul_f32_e32 v171, 0xbfb8aa3b, v171
	v_exp_f32_e32 v176, v176
	v_mul_f32_e32 v177, 0xbfb8aa3b, v177
	v_exp_f32_e32 v171, v171
	v_exp_f32_e32 v177, v177
	v_add_f32_e32 v159, 1.0, v159
	v_add_f32_e32 v165, 1.0, v165
	v_rcp_f32_e32 v159, v159
	v_add_f32_e32 v163, 1.0, v163
	v_rcp_f32_e32 v165, v165
	v_add_f32_e32 v167, 1.0, v167
	v_add_f32_e32 v169, 1.0, v169
	v_add_f32_e32 v176, 1.0, v176
	v_rcp_f32_e32 v163, v163
	v_rcp_f32_e32 v167, v167
	v_rcp_f32_e32 v169, v169
	v_add_f32_e32 v171, 1.0, v171
	v_rcp_f32_e32 v176, v176
	v_add_f32_e32 v177, 1.0, v177
	v_rcp_f32_e32 v171, v171
	v_rcp_f32_e32 v177, v177
	v_fma_f32 v159, v159, s31, 0.5
	v_fma_f32 v165, v165, s31, 0.5
	v_max_f32_e32 v159, 1.0, v159
	v_fma_f32 v163, v163, s31, 0.5
	v_max_f32_e32 v165, 1.0, v165
	v_fma_f32 v167, v167, s31, 0.5
	v_fma_f32 v169, v169, s31, 0.5
	v_fma_f32 v176, v176, s31, 0.5
	v_cvt_u32_f32_e32 v159, v159
	v_max_f32_e32 v163, 1.0, v163
	v_cvt_u32_f32_e32 v165, v165
	v_max_f32_e32 v167, 1.0, v167
	v_max_f32_e32 v169, 1.0, v169
	v_fma_f32 v171, v171, s31, 0.5
	v_max_f32_e32 v176, 1.0, v176
	v_fma_f32 v177, v177, s31, 0.5
	v_cvt_u32_f32_e32 v163, v163
	v_cvt_u32_f32_e32 v167, v167
	v_cvt_u32_f32_sdwa v169, v169 dst_sel:WORD_1 dst_unused:UNUSED_PAD src0_sel:DWORD
	v_max_f32_e32 v171, 1.0, v171
	v_cvt_u32_f32_sdwa v176, v176 dst_sel:BYTE_3 dst_unused:UNUSED_PAD src0_sel:DWORD
	v_max_f32_e32 v177, 1.0, v177
	v_cvt_u32_f32_sdwa v171, v171 dst_sel:WORD_1 dst_unused:UNUSED_PAD src0_sel:DWORD
	v_cvt_u32_f32_sdwa v177, v177 dst_sel:BYTE_3 dst_unused:UNUSED_PAD src0_sel:DWORD
	v_lshl_or_b32 v159, v165, 8, v159
	v_or3_b32 v176, v159, v169, v176
	v_lshl_or_b32 v159, v167, 8, v163
	v_or3_b32 v177, v159, v171, v177
	v_mul_f32_e32 v159, v102, v162
	v_mul_f32_e32 v163, v103, v162
	global_store_dwordx2 v[174:175], v[176:177], off offset:128
	v_lshlrev_b64 v[174:175], 12, v[160:161]
	v_mul_f32_e32 v159, 0xbfb8aa3b, v159
	v_mul_f32_e32 v161, v94, v162
	v_mul_f32_e32 v163, 0xbfb8aa3b, v163
	v_mul_f32_e32 v165, v95, v162
	v_mul_f32_e32 v167, v104, v162
	v_mul_f32_e32 v171, v105, v162
	v_exp_f32_e32 v159, v159
	v_mul_f32_e32 v161, 0xbfb8aa3b, v161
	v_exp_f32_e32 v163, v163
	v_mul_f32_e32 v165, 0xbfb8aa3b, v165
	v_mul_f32_e32 v167, 0xbfb8aa3b, v167
	v_mul_f32_e32 v169, v96, v162
	v_mul_f32_e32 v171, 0xbfb8aa3b, v171
	v_mul_f32_e32 v176, v97, v162
	v_exp_f32_e32 v161, v161
	v_exp_f32_e32 v165, v165
	v_exp_f32_e32 v167, v167
	v_mul_f32_e32 v169, 0xbfb8aa3b, v169
	v_exp_f32_e32 v171, v171
	v_mul_f32_e32 v176, 0xbfb8aa3b, v176
	v_exp_f32_e32 v169, v169
	v_exp_f32_e32 v176, v176
	v_add_f32_e32 v159, 1.0, v159
	v_add_f32_e32 v163, 1.0, v163
	v_rcp_f32_e32 v159, v159
	v_add_f32_e32 v161, 1.0, v161
	v_rcp_f32_e32 v163, v163
	v_add_f32_e32 v165, 1.0, v165
	v_add_f32_e32 v167, 1.0, v167
	v_add_f32_e32 v171, 1.0, v171
	v_rcp_f32_e32 v161, v161
	v_rcp_f32_e32 v165, v165
	v_rcp_f32_e32 v167, v167
	v_add_f32_e32 v169, 1.0, v169
	v_rcp_f32_e32 v171, v171
	v_add_f32_e32 v176, 1.0, v176
	v_rcp_f32_e32 v169, v169
	v_rcp_f32_e32 v176, v176
	v_fma_f32 v159, v159, s31, 0.5
	v_fma_f32 v163, v163, s31, 0.5
	v_max_f32_e32 v159, 1.0, v159
	v_fma_f32 v161, v161, s31, 0.5
	v_max_f32_e32 v163, 1.0, v163
	v_fma_f32 v165, v165, s31, 0.5
	v_fma_f32 v167, v167, s31, 0.5
	v_fma_f32 v171, v171, s31, 0.5
	v_cvt_u32_f32_e32 v159, v159
	v_max_f32_e32 v161, 1.0, v161
	v_cvt_u32_f32_e32 v163, v163
	v_max_f32_e32 v165, 1.0, v165
	v_max_f32_e32 v167, 1.0, v167
	v_fma_f32 v169, v169, s31, 0.5
	v_max_f32_e32 v171, 1.0, v171
	v_fma_f32 v176, v176, s31, 0.5
	v_cvt_u32_f32_e32 v161, v161
	v_cvt_u32_f32_e32 v165, v165
	v_cvt_u32_f32_sdwa v167, v167 dst_sel:WORD_1 dst_unused:UNUSED_PAD src0_sel:DWORD
	v_max_f32_e32 v169, 1.0, v169
	v_cvt_u32_f32_sdwa v171, v171 dst_sel:BYTE_3 dst_unused:UNUSED_PAD src0_sel:DWORD
	v_max_f32_e32 v176, 1.0, v176
	v_cvt_u32_f32_sdwa v169, v169 dst_sel:WORD_1 dst_unused:UNUSED_PAD src0_sel:DWORD
	v_cvt_u32_f32_sdwa v177, v176 dst_sel:BYTE_3 dst_unused:UNUSED_PAD src0_sel:DWORD
	v_lshl_or_b32 v159, v163, 8, v159
	v_or3_b32 v176, v159, v167, v171
	v_lshl_or_b32 v159, v165, 8, v161
	v_lshl_add_u64 v[174:175], s[22:23], 0, v[174:175]
	v_or3_b32 v177, v159, v169, v177
	v_mul_f32_e32 v159, v82, v162
	v_mul_f32_e32 v163, v83, v162
	v_lshl_add_u64 v[174:175], v[174:175], 0, v[172:173]
	v_mul_f32_e32 v159, 0xbfb8aa3b, v159
	v_mul_f32_e32 v161, v74, v162
	v_mul_f32_e32 v163, 0xbfb8aa3b, v163
	v_mul_f32_e32 v165, v75, v162
	v_mul_f32_e32 v167, v84, v162
	v_mul_f32_e32 v171, v85, v162
	v_exp_f32_e32 v159, v159
	v_mul_f32_e32 v161, 0xbfb8aa3b, v161
	global_store_dwordx2 v[174:175], v[176:177], off
	v_exp_f32_e32 v163, v163
	v_mul_f32_e32 v165, 0xbfb8aa3b, v165
	v_mul_f32_e32 v167, 0xbfb8aa3b, v167
	v_mul_f32_e32 v169, v76, v162
	v_mul_f32_e32 v171, 0xbfb8aa3b, v171
	v_mul_f32_e32 v176, v77, v162
	v_exp_f32_e32 v161, v161
	v_exp_f32_e32 v165, v165
	v_exp_f32_e32 v167, v167
	v_mul_f32_e32 v169, 0xbfb8aa3b, v169
	v_exp_f32_e32 v171, v171
	v_mul_f32_e32 v176, 0xbfb8aa3b, v176
	v_exp_f32_e32 v169, v169
	v_exp_f32_e32 v176, v176
	v_add_f32_e32 v159, 1.0, v159
	v_add_f32_e32 v163, 1.0, v163
	v_rcp_f32_e32 v159, v159
	v_add_f32_e32 v161, 1.0, v161
	v_rcp_f32_e32 v163, v163
	v_add_f32_e32 v165, 1.0, v165
	v_add_f32_e32 v167, 1.0, v167
	v_add_f32_e32 v171, 1.0, v171
	v_rcp_f32_e32 v161, v161
	v_rcp_f32_e32 v165, v165
	v_rcp_f32_e32 v167, v167
	v_add_f32_e32 v169, 1.0, v169
	v_rcp_f32_e32 v171, v171
	v_add_f32_e32 v176, 1.0, v176
	v_rcp_f32_e32 v169, v169
	v_rcp_f32_e32 v176, v176
	v_fma_f32 v159, v159, s31, 0.5
	v_fma_f32 v163, v163, s31, 0.5
	v_max_f32_e32 v159, 1.0, v159
	v_fma_f32 v161, v161, s31, 0.5
	v_max_f32_e32 v163, 1.0, v163
	v_fma_f32 v165, v165, s31, 0.5
	v_fma_f32 v167, v167, s31, 0.5
	v_fma_f32 v171, v171, s31, 0.5
	v_cvt_u32_f32_e32 v159, v159
	v_max_f32_e32 v161, 1.0, v161
	v_cvt_u32_f32_e32 v163, v163
	v_max_f32_e32 v165, 1.0, v165
	v_max_f32_e32 v167, 1.0, v167
	v_fma_f32 v169, v169, s31, 0.5
	v_max_f32_e32 v171, 1.0, v171
	v_fma_f32 v176, v176, s31, 0.5
	v_cvt_u32_f32_e32 v161, v161
	v_cvt_u32_f32_e32 v165, v165
	v_cvt_u32_f32_sdwa v167, v167 dst_sel:WORD_1 dst_unused:UNUSED_PAD src0_sel:DWORD
	v_max_f32_e32 v169, 1.0, v169
	v_cvt_u32_f32_sdwa v171, v171 dst_sel:BYTE_3 dst_unused:UNUSED_PAD src0_sel:DWORD
	v_max_f32_e32 v176, 1.0, v176
	v_cvt_u32_f32_sdwa v169, v169 dst_sel:WORD_1 dst_unused:UNUSED_PAD src0_sel:DWORD
	v_cvt_u32_f32_sdwa v177, v176 dst_sel:BYTE_3 dst_unused:UNUSED_PAD src0_sel:DWORD
	v_lshl_or_b32 v159, v163, 8, v159
	v_or3_b32 v176, v159, v167, v171
	v_lshl_or_b32 v159, v165, 8, v161
	v_or3_b32 v177, v159, v169, v177
	global_store_dwordx2 v[174:175], v[176:177], off offset:128
	v_lshlrev_b64 v[174:175], 12, v[154:155]
	v_mul_f32_e32 v155, v86, v158
	v_mul_f32_e32 v161, v87, v158
	v_mul_f32_e32 v155, 0xbfb8aa3b, v155
	v_mul_f32_e32 v159, v78, v158
	v_mul_f32_e32 v161, 0xbfb8aa3b, v161
	v_mul_f32_e32 v163, v79, v158
	v_mul_f32_e32 v165, v88, v158
	v_mul_f32_e32 v169, v89, v158
	v_exp_f32_e32 v155, v155
	v_mul_f32_e32 v159, 0xbfb8aa3b, v159
	v_exp_f32_e32 v161, v161
	v_mul_f32_e32 v163, 0xbfb8aa3b, v163
	v_mul_f32_e32 v165, 0xbfb8aa3b, v165
	v_mul_f32_e32 v167, v80, v158
	v_mul_f32_e32 v169, 0xbfb8aa3b, v169
	v_mul_f32_e32 v171, v81, v158
	v_exp_f32_e32 v159, v159
	v_exp_f32_e32 v163, v163
	v_exp_f32_e32 v165, v165
	v_mul_f32_e32 v167, 0xbfb8aa3b, v167
	v_exp_f32_e32 v169, v169
	v_mul_f32_e32 v171, 0xbfb8aa3b, v171
	v_exp_f32_e32 v167, v167
	v_exp_f32_e32 v171, v171
	v_add_f32_e32 v155, 1.0, v155
	v_add_f32_e32 v161, 1.0, v161
	v_rcp_f32_e32 v155, v155
	v_add_f32_e32 v159, 1.0, v159
	v_rcp_f32_e32 v161, v161
	v_add_f32_e32 v163, 1.0, v163
	v_add_f32_e32 v165, 1.0, v165
	v_add_f32_e32 v169, 1.0, v169
	v_rcp_f32_e32 v159, v159
	v_rcp_f32_e32 v163, v163
	v_rcp_f32_e32 v165, v165
	v_add_f32_e32 v167, 1.0, v167
	v_rcp_f32_e32 v169, v169
	v_add_f32_e32 v171, 1.0, v171
	v_rcp_f32_e32 v167, v167
	v_rcp_f32_e32 v171, v171
	v_fma_f32 v155, v155, s31, 0.5
	v_fma_f32 v161, v161, s31, 0.5
	v_max_f32_e32 v155, 1.0, v155
	v_fma_f32 v159, v159, s31, 0.5
	v_max_f32_e32 v161, 1.0, v161
	v_fma_f32 v163, v163, s31, 0.5
	v_fma_f32 v165, v165, s31, 0.5
	v_fma_f32 v169, v169, s31, 0.5
	v_cvt_u32_f32_e32 v155, v155
	v_max_f32_e32 v159, 1.0, v159
	v_cvt_u32_f32_e32 v161, v161
	v_max_f32_e32 v163, 1.0, v163
	v_max_f32_e32 v165, 1.0, v165
	v_fma_f32 v167, v167, s31, 0.5
	v_max_f32_e32 v169, 1.0, v169
	v_fma_f32 v171, v171, s31, 0.5
	v_cvt_u32_f32_e32 v159, v159
	v_cvt_u32_f32_e32 v163, v163
	v_cvt_u32_f32_sdwa v165, v165 dst_sel:WORD_1 dst_unused:UNUSED_PAD src0_sel:DWORD
	v_max_f32_e32 v167, 1.0, v167
	v_cvt_u32_f32_sdwa v169, v169 dst_sel:BYTE_3 dst_unused:UNUSED_PAD src0_sel:DWORD
	v_max_f32_e32 v171, 1.0, v171
	v_cvt_u32_f32_sdwa v167, v167 dst_sel:WORD_1 dst_unused:UNUSED_PAD src0_sel:DWORD
	v_cvt_u32_f32_sdwa v171, v171 dst_sel:BYTE_3 dst_unused:UNUSED_PAD src0_sel:DWORD
	v_lshl_or_b32 v155, v161, 8, v155
	v_or3_b32 v176, v155, v165, v169
	v_lshl_or_b32 v155, v163, 8, v159
	v_or3_b32 v177, v155, v167, v171
	v_mul_f32_e32 v155, v70, v158
	v_mul_f32_e32 v161, v71, v158
	v_mul_f32_e32 v155, 0xbfb8aa3b, v155
	v_mul_f32_e32 v159, v66, v158
	v_mul_f32_e32 v161, 0xbfb8aa3b, v161
	v_mul_f32_e32 v163, v67, v158
	v_mul_f32_e32 v165, v72, v158
	v_mul_f32_e32 v169, v73, v158
	v_exp_f32_e32 v155, v155
	v_mul_f32_e32 v159, 0xbfb8aa3b, v159
	v_exp_f32_e32 v161, v161
	v_mul_f32_e32 v163, 0xbfb8aa3b, v163
	v_mul_f32_e32 v165, 0xbfb8aa3b, v165
	v_mul_f32_e32 v167, v68, v158
	v_mul_f32_e32 v169, 0xbfb8aa3b, v169
	v_mul_f32_e32 v171, v69, v158
	v_exp_f32_e32 v159, v159
	v_exp_f32_e32 v163, v163
	v_exp_f32_e32 v165, v165
	v_mul_f32_e32 v167, 0xbfb8aa3b, v167
	v_exp_f32_e32 v169, v169
	v_mul_f32_e32 v171, 0xbfb8aa3b, v171
	v_exp_f32_e32 v167, v167
	v_exp_f32_e32 v171, v171
	v_add_f32_e32 v155, 1.0, v155
	v_add_f32_e32 v161, 1.0, v161
	v_rcp_f32_e32 v155, v155
	v_add_f32_e32 v159, 1.0, v159
	v_rcp_f32_e32 v161, v161
	v_add_f32_e32 v163, 1.0, v163
	v_add_f32_e32 v165, 1.0, v165
	v_add_f32_e32 v169, 1.0, v169
	v_rcp_f32_e32 v159, v159
	v_rcp_f32_e32 v163, v163
	v_rcp_f32_e32 v165, v165
	v_add_f32_e32 v167, 1.0, v167
	v_rcp_f32_e32 v169, v169
	v_add_f32_e32 v171, 1.0, v171
	v_rcp_f32_e32 v167, v167
	v_rcp_f32_e32 v171, v171
	v_fma_f32 v155, v155, s31, 0.5
	v_fma_f32 v161, v161, s31, 0.5
	v_max_f32_e32 v155, 1.0, v155
	v_fma_f32 v159, v159, s31, 0.5
	v_max_f32_e32 v161, 1.0, v161
	v_fma_f32 v163, v163, s31, 0.5
	v_fma_f32 v165, v165, s31, 0.5
	v_fma_f32 v169, v169, s31, 0.5
	v_cvt_u32_f32_e32 v155, v155
	v_max_f32_e32 v159, 1.0, v159
	v_cvt_u32_f32_e32 v161, v161
	v_max_f32_e32 v163, 1.0, v163
	v_max_f32_e32 v165, 1.0, v165
	v_fma_f32 v167, v167, s31, 0.5
	v_max_f32_e32 v169, 1.0, v169
	v_fma_f32 v171, v171, s31, 0.5
	v_cvt_u32_f32_e32 v159, v159
	v_cvt_u32_f32_e32 v163, v163
	v_cvt_u32_f32_sdwa v165, v165 dst_sel:WORD_1 dst_unused:UNUSED_PAD src0_sel:DWORD
	v_max_f32_e32 v167, 1.0, v167
	v_cvt_u32_f32_sdwa v169, v169 dst_sel:BYTE_3 dst_unused:UNUSED_PAD src0_sel:DWORD
	v_max_f32_e32 v171, 1.0, v171
	v_cvt_u32_f32_sdwa v167, v167 dst_sel:WORD_1 dst_unused:UNUSED_PAD src0_sel:DWORD
	v_cvt_u32_f32_sdwa v171, v171 dst_sel:BYTE_3 dst_unused:UNUSED_PAD src0_sel:DWORD
	v_lshl_add_u64 v[174:175], s[22:23], 0, v[174:175]
	v_lshl_add_u64 v[174:175], v[174:175], 0, v[172:173]
	v_lshl_or_b32 v155, v161, 8, v155
	global_store_dwordx2 v[174:175], v[176:177], off
	v_or3_b32 v176, v155, v165, v169
	v_lshl_or_b32 v155, v163, 8, v159
	v_or3_b32 v177, v155, v167, v171
	v_mul_f32_e32 v155, v62, v152
	v_mul_f32_e32 v159, v63, v152
	global_store_dwordx2 v[174:175], v[176:177], off offset:128
	v_lshlrev_b64 v[174:175], 12, v[156:157]
	v_mul_f32_e32 v155, 0xbfb8aa3b, v155
	v_mul_f32_e32 v157, v58, v152
	v_mul_f32_e32 v159, 0xbfb8aa3b, v159
	v_mul_f32_e32 v161, v59, v152
	v_mul_f32_e32 v163, v64, v152
	v_mul_f32_e32 v167, v65, v152
	v_exp_f32_e32 v155, v155
	v_mul_f32_e32 v157, 0xbfb8aa3b, v157
	v_exp_f32_e32 v159, v159
	v_mul_f32_e32 v161, 0xbfb8aa3b, v161
	v_mul_f32_e32 v163, 0xbfb8aa3b, v163
	v_mul_f32_e32 v165, v60, v152
	v_mul_f32_e32 v167, 0xbfb8aa3b, v167
	v_mul_f32_e32 v169, v61, v152
	v_exp_f32_e32 v157, v157
	v_exp_f32_e32 v161, v161
	v_exp_f32_e32 v163, v163
	v_mul_f32_e32 v165, 0xbfb8aa3b, v165
	v_exp_f32_e32 v167, v167
	v_mul_f32_e32 v169, 0xbfb8aa3b, v169
	v_exp_f32_e32 v165, v165
	v_exp_f32_e32 v169, v169
	v_add_f32_e32 v155, 1.0, v155
	v_add_f32_e32 v159, 1.0, v159
	v_rcp_f32_e32 v155, v155
	v_add_f32_e32 v157, 1.0, v157
	v_rcp_f32_e32 v159, v159
	v_add_f32_e32 v161, 1.0, v161
	v_add_f32_e32 v163, 1.0, v163
	v_add_f32_e32 v167, 1.0, v167
	v_rcp_f32_e32 v157, v157
	v_rcp_f32_e32 v161, v161
	v_rcp_f32_e32 v163, v163
	v_add_f32_e32 v165, 1.0, v165
	v_rcp_f32_e32 v167, v167
	v_add_f32_e32 v169, 1.0, v169
	v_rcp_f32_e32 v165, v165
	v_rcp_f32_e32 v169, v169
	v_fma_f32 v155, v155, s31, 0.5
	v_fma_f32 v159, v159, s31, 0.5
	v_max_f32_e32 v155, 1.0, v155
	v_fma_f32 v157, v157, s31, 0.5
	v_max_f32_e32 v159, 1.0, v159
	v_fma_f32 v161, v161, s31, 0.5
	v_fma_f32 v163, v163, s31, 0.5
	v_fma_f32 v167, v167, s31, 0.5
	v_cvt_u32_f32_e32 v155, v155
	v_max_f32_e32 v157, 1.0, v157
	v_cvt_u32_f32_e32 v159, v159
	v_max_f32_e32 v161, 1.0, v161
	v_max_f32_e32 v163, 1.0, v163
	v_fma_f32 v165, v165, s31, 0.5
	v_max_f32_e32 v167, 1.0, v167
	v_fma_f32 v169, v169, s31, 0.5
	v_cvt_u32_f32_e32 v157, v157
	v_cvt_u32_f32_e32 v161, v161
	v_cvt_u32_f32_sdwa v163, v163 dst_sel:WORD_1 dst_unused:UNUSED_PAD src0_sel:DWORD
	v_max_f32_e32 v165, 1.0, v165
	v_cvt_u32_f32_sdwa v167, v167 dst_sel:BYTE_3 dst_unused:UNUSED_PAD src0_sel:DWORD
	v_max_f32_e32 v169, 1.0, v169
	v_cvt_u32_f32_sdwa v165, v165 dst_sel:WORD_1 dst_unused:UNUSED_PAD src0_sel:DWORD
	v_cvt_u32_f32_sdwa v169, v169 dst_sel:BYTE_3 dst_unused:UNUSED_PAD src0_sel:DWORD
	v_lshl_or_b32 v155, v159, 8, v155
	v_or3_b32 v176, v155, v163, v167
	v_lshl_or_b32 v155, v161, 8, v157
	v_or3_b32 v177, v155, v165, v169
	v_mul_f32_e32 v155, v50, v152
	v_mul_f32_e32 v159, v51, v152
	v_mul_f32_e32 v155, 0xbfb8aa3b, v155
	v_mul_f32_e32 v157, v42, v152
	v_mul_f32_e32 v159, 0xbfb8aa3b, v159
	v_mul_f32_e32 v161, v43, v152
	v_mul_f32_e32 v163, v52, v152
	v_mul_f32_e32 v167, v53, v152
	v_exp_f32_e32 v155, v155
	v_mul_f32_e32 v157, 0xbfb8aa3b, v157
	v_exp_f32_e32 v159, v159
	v_mul_f32_e32 v161, 0xbfb8aa3b, v161
	v_mul_f32_e32 v163, 0xbfb8aa3b, v163
	v_mul_f32_e32 v165, v44, v152
	v_mul_f32_e32 v167, 0xbfb8aa3b, v167
	v_mul_f32_e32 v169, v45, v152
	v_exp_f32_e32 v157, v157
	v_exp_f32_e32 v161, v161
	v_exp_f32_e32 v163, v163
	v_mul_f32_e32 v165, 0xbfb8aa3b, v165
	v_exp_f32_e32 v167, v167
	v_mul_f32_e32 v169, 0xbfb8aa3b, v169
	v_exp_f32_e32 v165, v165
	v_exp_f32_e32 v169, v169
	v_add_f32_e32 v155, 1.0, v155
	v_add_f32_e32 v159, 1.0, v159
	v_rcp_f32_e32 v155, v155
	v_add_f32_e32 v157, 1.0, v157
	v_rcp_f32_e32 v159, v159
	v_add_f32_e32 v161, 1.0, v161
	v_add_f32_e32 v163, 1.0, v163
	v_add_f32_e32 v167, 1.0, v167
	v_rcp_f32_e32 v157, v157
	v_rcp_f32_e32 v161, v161
	v_rcp_f32_e32 v163, v163
	v_add_f32_e32 v165, 1.0, v165
	v_rcp_f32_e32 v167, v167
	v_add_f32_e32 v169, 1.0, v169
	v_rcp_f32_e32 v165, v165
	v_rcp_f32_e32 v169, v169
	v_fma_f32 v155, v155, s31, 0.5
	v_fma_f32 v159, v159, s31, 0.5
	v_max_f32_e32 v155, 1.0, v155
	v_fma_f32 v157, v157, s31, 0.5
	v_max_f32_e32 v159, 1.0, v159
	v_fma_f32 v161, v161, s31, 0.5
	v_fma_f32 v163, v163, s31, 0.5
	v_fma_f32 v167, v167, s31, 0.5
	v_cvt_u32_f32_e32 v155, v155
	v_max_f32_e32 v157, 1.0, v157
	v_cvt_u32_f32_e32 v159, v159
	v_max_f32_e32 v161, 1.0, v161
	v_max_f32_e32 v163, 1.0, v163
	v_fma_f32 v165, v165, s31, 0.5
	v_max_f32_e32 v167, 1.0, v167
	v_fma_f32 v169, v169, s31, 0.5
	v_cvt_u32_f32_e32 v157, v157
	v_cvt_u32_f32_e32 v161, v161
	v_cvt_u32_f32_sdwa v163, v163 dst_sel:WORD_1 dst_unused:UNUSED_PAD src0_sel:DWORD
	v_max_f32_e32 v165, 1.0, v165
	v_cvt_u32_f32_sdwa v167, v167 dst_sel:BYTE_3 dst_unused:UNUSED_PAD src0_sel:DWORD
	v_max_f32_e32 v169, 1.0, v169
	v_cvt_u32_f32_sdwa v165, v165 dst_sel:WORD_1 dst_unused:UNUSED_PAD src0_sel:DWORD
	v_cvt_u32_f32_sdwa v169, v169 dst_sel:BYTE_3 dst_unused:UNUSED_PAD src0_sel:DWORD
	v_lshl_add_u64 v[174:175], s[22:23], 0, v[174:175]
	v_lshl_add_u64 v[174:175], v[174:175], 0, v[172:173]
	v_lshl_or_b32 v155, v159, 8, v155
	global_store_dwordx2 v[174:175], v[176:177], off
	v_or3_b32 v176, v155, v163, v167
	v_lshl_or_b32 v155, v161, 8, v157
	v_or3_b32 v177, v155, v165, v169
	global_store_dwordx2 v[174:175], v[176:177], off offset:128
	v_lshlrev_b64 v[174:175], 12, v[150:151]
	v_mul_f32_e32 v151, v54, v148
	v_mul_f32_e32 v157, v55, v148
	v_mul_f32_e32 v151, 0xbfb8aa3b, v151
	v_mul_f32_e32 v155, v46, v148
	v_mul_f32_e32 v157, 0xbfb8aa3b, v157
	v_mul_f32_e32 v159, v47, v148
	v_mul_f32_e32 v161, v56, v148
	v_mul_f32_e32 v165, v57, v148
	v_exp_f32_e32 v151, v151
	v_mul_f32_e32 v155, 0xbfb8aa3b, v155
	v_exp_f32_e32 v157, v157
	v_mul_f32_e32 v159, 0xbfb8aa3b, v159
	v_mul_f32_e32 v161, 0xbfb8aa3b, v161
	v_mul_f32_e32 v163, v48, v148
	v_mul_f32_e32 v165, 0xbfb8aa3b, v165
	v_mul_f32_e32 v167, v49, v148
	v_exp_f32_e32 v155, v155
	v_exp_f32_e32 v159, v159
	v_exp_f32_e32 v161, v161
	v_mul_f32_e32 v163, 0xbfb8aa3b, v163
	v_exp_f32_e32 v165, v165
	v_mul_f32_e32 v167, 0xbfb8aa3b, v167
	v_exp_f32_e32 v163, v163
	v_exp_f32_e32 v167, v167
	v_add_f32_e32 v151, 1.0, v151
	v_add_f32_e32 v157, 1.0, v157
	v_rcp_f32_e32 v151, v151
	v_add_f32_e32 v155, 1.0, v155
	v_rcp_f32_e32 v157, v157
	v_add_f32_e32 v159, 1.0, v159
	v_add_f32_e32 v161, 1.0, v161
	v_add_f32_e32 v165, 1.0, v165
	v_rcp_f32_e32 v155, v155
	v_rcp_f32_e32 v159, v159
	v_rcp_f32_e32 v161, v161
	v_add_f32_e32 v163, 1.0, v163
	v_rcp_f32_e32 v165, v165
	v_add_f32_e32 v167, 1.0, v167
	v_rcp_f32_e32 v163, v163
	v_rcp_f32_e32 v167, v167
	v_fma_f32 v151, v151, s31, 0.5
	v_fma_f32 v157, v157, s31, 0.5
	v_max_f32_e32 v151, 1.0, v151
	v_fma_f32 v155, v155, s31, 0.5
	v_max_f32_e32 v157, 1.0, v157
	v_fma_f32 v159, v159, s31, 0.5
	v_fma_f32 v161, v161, s31, 0.5
	v_fma_f32 v165, v165, s31, 0.5
	v_cvt_u32_f32_e32 v151, v151
	v_max_f32_e32 v155, 1.0, v155
	v_cvt_u32_f32_e32 v157, v157
	v_max_f32_e32 v159, 1.0, v159
	v_max_f32_e32 v161, 1.0, v161
	v_fma_f32 v163, v163, s31, 0.5
	v_max_f32_e32 v165, 1.0, v165
	v_fma_f32 v167, v167, s31, 0.5
	v_cvt_u32_f32_e32 v155, v155
	v_cvt_u32_f32_e32 v159, v159
	v_cvt_u32_f32_sdwa v161, v161 dst_sel:WORD_1 dst_unused:UNUSED_PAD src0_sel:DWORD
	v_max_f32_e32 v163, 1.0, v163
	v_cvt_u32_f32_sdwa v165, v165 dst_sel:BYTE_3 dst_unused:UNUSED_PAD src0_sel:DWORD
	v_max_f32_e32 v167, 1.0, v167
	v_cvt_u32_f32_sdwa v163, v163 dst_sel:WORD_1 dst_unused:UNUSED_PAD src0_sel:DWORD
	v_cvt_u32_f32_sdwa v167, v167 dst_sel:BYTE_3 dst_unused:UNUSED_PAD src0_sel:DWORD
	v_lshl_or_b32 v151, v157, 8, v151
	v_or3_b32 v176, v151, v161, v165
	v_lshl_or_b32 v151, v159, 8, v155
	v_or3_b32 v177, v151, v163, v167
	v_mul_f32_e32 v151, v34, v148
	v_mul_f32_e32 v157, v35, v148
	v_mul_f32_e32 v151, 0xbfb8aa3b, v151
	v_mul_f32_e32 v155, v26, v148
	v_mul_f32_e32 v157, 0xbfb8aa3b, v157
	v_mul_f32_e32 v159, v27, v148
	v_mul_f32_e32 v161, v36, v148
	v_mul_f32_e32 v165, v37, v148
	v_exp_f32_e32 v151, v151
	v_mul_f32_e32 v155, 0xbfb8aa3b, v155
	v_exp_f32_e32 v157, v157
	v_mul_f32_e32 v159, 0xbfb8aa3b, v159
	v_mul_f32_e32 v161, 0xbfb8aa3b, v161
	v_mul_f32_e32 v163, v28, v148
	v_mul_f32_e32 v165, 0xbfb8aa3b, v165
	v_mul_f32_e32 v167, v29, v148
	v_exp_f32_e32 v155, v155
	v_exp_f32_e32 v159, v159
	v_exp_f32_e32 v161, v161
	v_mul_f32_e32 v163, 0xbfb8aa3b, v163
	v_exp_f32_e32 v165, v165
	v_mul_f32_e32 v167, 0xbfb8aa3b, v167
	v_exp_f32_e32 v163, v163
	v_exp_f32_e32 v167, v167
	v_add_f32_e32 v151, 1.0, v151
	v_add_f32_e32 v157, 1.0, v157
	v_rcp_f32_e32 v151, v151
	v_add_f32_e32 v155, 1.0, v155
	v_rcp_f32_e32 v157, v157
	v_add_f32_e32 v159, 1.0, v159
	v_add_f32_e32 v161, 1.0, v161
	v_add_f32_e32 v165, 1.0, v165
	v_rcp_f32_e32 v155, v155
	v_rcp_f32_e32 v159, v159
	v_rcp_f32_e32 v161, v161
	v_add_f32_e32 v163, 1.0, v163
	v_rcp_f32_e32 v165, v165
	v_add_f32_e32 v167, 1.0, v167
	v_rcp_f32_e32 v163, v163
	v_rcp_f32_e32 v167, v167
	v_fma_f32 v151, v151, s31, 0.5
	v_fma_f32 v157, v157, s31, 0.5
	v_max_f32_e32 v151, 1.0, v151
	v_fma_f32 v155, v155, s31, 0.5
	v_max_f32_e32 v157, 1.0, v157
	v_fma_f32 v159, v159, s31, 0.5
	v_fma_f32 v161, v161, s31, 0.5
	v_fma_f32 v165, v165, s31, 0.5
	v_cvt_u32_f32_e32 v151, v151
	v_max_f32_e32 v155, 1.0, v155
	v_cvt_u32_f32_e32 v157, v157
	v_max_f32_e32 v159, 1.0, v159
	v_max_f32_e32 v161, 1.0, v161
	v_fma_f32 v163, v163, s31, 0.5
	v_max_f32_e32 v165, 1.0, v165
	v_fma_f32 v167, v167, s31, 0.5
	v_cvt_u32_f32_e32 v155, v155
	v_cvt_u32_f32_e32 v159, v159
	v_cvt_u32_f32_sdwa v161, v161 dst_sel:WORD_1 dst_unused:UNUSED_PAD src0_sel:DWORD
	v_max_f32_e32 v163, 1.0, v163
	v_cvt_u32_f32_sdwa v165, v165 dst_sel:BYTE_3 dst_unused:UNUSED_PAD src0_sel:DWORD
	v_max_f32_e32 v167, 1.0, v167
	v_cvt_u32_f32_sdwa v163, v163 dst_sel:WORD_1 dst_unused:UNUSED_PAD src0_sel:DWORD
	v_cvt_u32_f32_sdwa v167, v167 dst_sel:BYTE_3 dst_unused:UNUSED_PAD src0_sel:DWORD
	v_lshl_add_u64 v[174:175], s[22:23], 0, v[174:175]
	v_lshl_add_u64 v[174:175], v[174:175], 0, v[172:173]
	v_lshl_or_b32 v151, v157, 8, v151
	global_store_dwordx2 v[174:175], v[176:177], off
	v_or3_b32 v176, v151, v161, v165
	v_lshl_or_b32 v151, v159, 8, v155
	v_or3_b32 v177, v151, v163, v167
	global_store_dwordx2 v[174:175], v[176:177], off offset:128
	v_lshlrev_b64 v[174:175], 12, v[146:147]
	v_mul_f32_e32 v147, v38, v144
	v_mul_f32_e32 v155, v39, v144
	v_mul_f32_e32 v147, 0xbfb8aa3b, v147
	v_mul_f32_e32 v151, v30, v144
	v_mul_f32_e32 v155, 0xbfb8aa3b, v155
	v_mul_f32_e32 v157, v31, v144
	v_mul_f32_e32 v159, v40, v144
	v_mul_f32_e32 v163, v41, v144
	v_exp_f32_e32 v147, v147
	v_mul_f32_e32 v151, 0xbfb8aa3b, v151
	v_exp_f32_e32 v155, v155
	v_mul_f32_e32 v157, 0xbfb8aa3b, v157
	v_mul_f32_e32 v159, 0xbfb8aa3b, v159
	v_mul_f32_e32 v161, v32, v144
	v_mul_f32_e32 v163, 0xbfb8aa3b, v163
	v_mul_f32_e32 v165, v33, v144
	v_exp_f32_e32 v151, v151
	v_exp_f32_e32 v157, v157
	v_exp_f32_e32 v159, v159
	v_mul_f32_e32 v161, 0xbfb8aa3b, v161
	v_exp_f32_e32 v163, v163
	v_mul_f32_e32 v165, 0xbfb8aa3b, v165
	v_exp_f32_e32 v161, v161
	v_exp_f32_e32 v165, v165
	v_add_f32_e32 v147, 1.0, v147
	v_add_f32_e32 v155, 1.0, v155
	v_rcp_f32_e32 v147, v147
	v_add_f32_e32 v151, 1.0, v151
	v_rcp_f32_e32 v155, v155
	v_add_f32_e32 v157, 1.0, v157
	v_add_f32_e32 v159, 1.0, v159
	v_add_f32_e32 v163, 1.0, v163
	v_rcp_f32_e32 v151, v151
	v_rcp_f32_e32 v157, v157
	v_rcp_f32_e32 v159, v159
	v_add_f32_e32 v161, 1.0, v161
	v_rcp_f32_e32 v163, v163
	v_add_f32_e32 v165, 1.0, v165
	v_rcp_f32_e32 v161, v161
	v_rcp_f32_e32 v165, v165
	v_fma_f32 v147, v147, s31, 0.5
	v_fma_f32 v155, v155, s31, 0.5
	v_max_f32_e32 v147, 1.0, v147
	v_fma_f32 v151, v151, s31, 0.5
	v_max_f32_e32 v155, 1.0, v155
	v_fma_f32 v157, v157, s31, 0.5
	v_fma_f32 v159, v159, s31, 0.5
	v_fma_f32 v163, v163, s31, 0.5
	v_cvt_u32_f32_e32 v147, v147
	v_max_f32_e32 v151, 1.0, v151
	v_cvt_u32_f32_e32 v155, v155
	v_max_f32_e32 v157, 1.0, v157
	v_max_f32_e32 v159, 1.0, v159
	v_fma_f32 v161, v161, s31, 0.5
	v_max_f32_e32 v163, 1.0, v163
	v_fma_f32 v165, v165, s31, 0.5
	v_cvt_u32_f32_e32 v151, v151
	v_cvt_u32_f32_e32 v157, v157
	v_cvt_u32_f32_sdwa v159, v159 dst_sel:WORD_1 dst_unused:UNUSED_PAD src0_sel:DWORD
	v_max_f32_e32 v161, 1.0, v161
	v_cvt_u32_f32_sdwa v163, v163 dst_sel:BYTE_3 dst_unused:UNUSED_PAD src0_sel:DWORD
	v_max_f32_e32 v165, 1.0, v165
	v_cvt_u32_f32_sdwa v161, v161 dst_sel:WORD_1 dst_unused:UNUSED_PAD src0_sel:DWORD
	v_cvt_u32_f32_sdwa v165, v165 dst_sel:BYTE_3 dst_unused:UNUSED_PAD src0_sel:DWORD
	v_lshl_or_b32 v147, v155, 8, v147
	v_or3_b32 v176, v147, v159, v163
	v_lshl_or_b32 v147, v157, 8, v151
	v_or3_b32 v177, v147, v161, v165
	v_mul_f32_e32 v147, v18, v144
	v_mul_f32_e32 v155, v19, v144
	v_mul_f32_e32 v147, 0xbfb8aa3b, v147
	v_mul_f32_e32 v151, v8, v144
	v_mul_f32_e32 v155, 0xbfb8aa3b, v155
	v_mul_f32_e32 v157, v9, v144
	v_mul_f32_e32 v159, v20, v144
	v_mul_f32_e32 v163, v21, v144
	v_exp_f32_e32 v147, v147
	v_mul_f32_e32 v151, 0xbfb8aa3b, v151
	v_exp_f32_e32 v155, v155
	v_mul_f32_e32 v157, 0xbfb8aa3b, v157
	v_mul_f32_e32 v159, 0xbfb8aa3b, v159
	v_mul_f32_e32 v161, v10, v144
	v_mul_f32_e32 v163, 0xbfb8aa3b, v163
	v_mul_f32_e32 v165, v11, v144
	v_exp_f32_e32 v151, v151
	v_exp_f32_e32 v157, v157
	v_exp_f32_e32 v159, v159
	v_mul_f32_e32 v161, 0xbfb8aa3b, v161
	v_exp_f32_e32 v163, v163
	v_mul_f32_e32 v165, 0xbfb8aa3b, v165
	v_exp_f32_e32 v161, v161
	v_exp_f32_e32 v165, v165
	v_add_f32_e32 v147, 1.0, v147
	v_add_f32_e32 v155, 1.0, v155
	v_rcp_f32_e32 v147, v147
	v_add_f32_e32 v151, 1.0, v151
	v_rcp_f32_e32 v155, v155
	v_add_f32_e32 v157, 1.0, v157
	v_add_f32_e32 v159, 1.0, v159
	v_add_f32_e32 v163, 1.0, v163
	v_rcp_f32_e32 v151, v151
	v_rcp_f32_e32 v157, v157
	v_rcp_f32_e32 v159, v159
	v_add_f32_e32 v161, 1.0, v161
	v_rcp_f32_e32 v163, v163
	v_add_f32_e32 v165, 1.0, v165
	v_rcp_f32_e32 v161, v161
	v_rcp_f32_e32 v165, v165
	v_fma_f32 v147, v147, s31, 0.5
	v_fma_f32 v155, v155, s31, 0.5
	v_max_f32_e32 v147, 1.0, v147
	v_fma_f32 v151, v151, s31, 0.5
	v_max_f32_e32 v155, 1.0, v155
	v_fma_f32 v157, v157, s31, 0.5
	v_fma_f32 v159, v159, s31, 0.5
	v_fma_f32 v163, v163, s31, 0.5
	v_cvt_u32_f32_e32 v147, v147
	v_max_f32_e32 v151, 1.0, v151
	v_cvt_u32_f32_e32 v155, v155
	v_max_f32_e32 v157, 1.0, v157
	v_max_f32_e32 v159, 1.0, v159
	v_fma_f32 v161, v161, s31, 0.5
	v_max_f32_e32 v163, 1.0, v163
	v_fma_f32 v165, v165, s31, 0.5
	v_cvt_u32_f32_e32 v151, v151
	v_cvt_u32_f32_e32 v157, v157
	v_cvt_u32_f32_sdwa v159, v159 dst_sel:WORD_1 dst_unused:UNUSED_PAD src0_sel:DWORD
	v_max_f32_e32 v161, 1.0, v161
	v_cvt_u32_f32_sdwa v163, v163 dst_sel:BYTE_3 dst_unused:UNUSED_PAD src0_sel:DWORD
	v_max_f32_e32 v165, 1.0, v165
	v_cvt_u32_f32_sdwa v161, v161 dst_sel:WORD_1 dst_unused:UNUSED_PAD src0_sel:DWORD
	v_cvt_u32_f32_sdwa v165, v165 dst_sel:BYTE_3 dst_unused:UNUSED_PAD src0_sel:DWORD
	v_lshl_add_u64 v[174:175], s[22:23], 0, v[174:175]
	v_lshl_add_u64 v[174:175], v[174:175], 0, v[172:173]
	v_lshl_or_b32 v147, v155, 8, v147
	global_store_dwordx2 v[174:175], v[176:177], off
	v_or3_b32 v176, v147, v159, v163
	v_lshl_or_b32 v147, v157, 8, v151
	v_or3_b32 v177, v147, v161, v165
	global_store_dwordx2 v[174:175], v[176:177], off offset:128
	v_lshlrev_b64 v[174:175], 12, v[142:143]
	v_mul_f32_e32 v143, v22, v140
	v_mul_f32_e32 v151, v23, v140
	v_mul_f32_e32 v143, 0xbfb8aa3b, v143
	v_mul_f32_e32 v147, v12, v140
	v_mul_f32_e32 v151, 0xbfb8aa3b, v151
	v_mul_f32_e32 v155, v13, v140
	v_mul_f32_e32 v157, v24, v140
	v_mul_f32_e32 v161, v25, v140
	v_exp_f32_e32 v143, v143
	v_mul_f32_e32 v147, 0xbfb8aa3b, v147
	v_exp_f32_e32 v151, v151
	v_mul_f32_e32 v155, 0xbfb8aa3b, v155
	v_mul_f32_e32 v157, 0xbfb8aa3b, v157
	v_mul_f32_e32 v159, v14, v140
	v_mul_f32_e32 v161, 0xbfb8aa3b, v161
	v_mul_f32_e32 v163, v15, v140
	v_exp_f32_e32 v147, v147
	v_exp_f32_e32 v155, v155
	v_exp_f32_e32 v157, v157
	v_mul_f32_e32 v159, 0xbfb8aa3b, v159
	v_exp_f32_e32 v161, v161
	v_mul_f32_e32 v163, 0xbfb8aa3b, v163
	v_exp_f32_e32 v159, v159
	v_exp_f32_e32 v163, v163
	v_add_f32_e32 v143, 1.0, v143
	v_add_f32_e32 v151, 1.0, v151
	v_rcp_f32_e32 v143, v143
	v_add_f32_e32 v147, 1.0, v147
	v_rcp_f32_e32 v151, v151
	v_add_f32_e32 v155, 1.0, v155
	v_add_f32_e32 v157, 1.0, v157
	v_add_f32_e32 v161, 1.0, v161
	v_rcp_f32_e32 v147, v147
	v_rcp_f32_e32 v155, v155
	v_rcp_f32_e32 v157, v157
	v_add_f32_e32 v159, 1.0, v159
	v_rcp_f32_e32 v161, v161
	v_add_f32_e32 v163, 1.0, v163
	v_rcp_f32_e32 v159, v159
	v_rcp_f32_e32 v163, v163
	v_fma_f32 v143, v143, s31, 0.5
	v_fma_f32 v151, v151, s31, 0.5
	v_max_f32_e32 v143, 1.0, v143
	v_fma_f32 v147, v147, s31, 0.5
	v_max_f32_e32 v151, 1.0, v151
	v_fma_f32 v155, v155, s31, 0.5
	v_fma_f32 v157, v157, s31, 0.5
	v_fma_f32 v161, v161, s31, 0.5
	v_cvt_u32_f32_e32 v143, v143
	v_max_f32_e32 v147, 1.0, v147
	v_cvt_u32_f32_e32 v151, v151
	v_max_f32_e32 v155, 1.0, v155
	v_max_f32_e32 v157, 1.0, v157
	v_fma_f32 v159, v159, s31, 0.5
	v_max_f32_e32 v161, 1.0, v161
	v_fma_f32 v163, v163, s31, 0.5
	v_cvt_u32_f32_e32 v147, v147
	v_cvt_u32_f32_e32 v155, v155
	v_cvt_u32_f32_sdwa v157, v157 dst_sel:WORD_1 dst_unused:UNUSED_PAD src0_sel:DWORD
	v_max_f32_e32 v159, 1.0, v159
	v_cvt_u32_f32_sdwa v161, v161 dst_sel:BYTE_3 dst_unused:UNUSED_PAD src0_sel:DWORD
	v_max_f32_e32 v163, 1.0, v163
	v_cvt_u32_f32_sdwa v159, v159 dst_sel:WORD_1 dst_unused:UNUSED_PAD src0_sel:DWORD
	v_cvt_u32_f32_sdwa v163, v163 dst_sel:BYTE_3 dst_unused:UNUSED_PAD src0_sel:DWORD
	v_lshl_or_b32 v143, v151, 8, v143
	v_or3_b32 v176, v143, v157, v161
	v_lshl_or_b32 v143, v155, 8, v147
	v_or3_b32 v177, v143, v159, v163
	v_mul_f32_e32 v143, v4, v140
	v_mul_f32_e32 v151, v5, v140
	v_mul_f32_e32 v143, 0xbfb8aa3b, v143
	v_mul_f32_e32 v147, v0, v140
	v_mul_f32_e32 v151, 0xbfb8aa3b, v151
	v_mul_f32_e32 v155, v1, v140
	v_mul_f32_e32 v157, v6, v140
	v_mul_f32_e32 v161, v7, v140
	v_exp_f32_e32 v143, v143
	v_mul_f32_e32 v147, 0xbfb8aa3b, v147
	v_exp_f32_e32 v151, v151
	v_mul_f32_e32 v155, 0xbfb8aa3b, v155
	v_mul_f32_e32 v157, 0xbfb8aa3b, v157
	v_mul_f32_e32 v159, v2, v140
	v_mul_f32_e32 v161, 0xbfb8aa3b, v161
	v_mul_f32_e32 v163, v3, v140
	v_exp_f32_e32 v147, v147
	v_exp_f32_e32 v155, v155
	v_exp_f32_e32 v157, v157
	v_mul_f32_e32 v159, 0xbfb8aa3b, v159
	v_exp_f32_e32 v161, v161
	v_mul_f32_e32 v163, 0xbfb8aa3b, v163
	v_exp_f32_e32 v159, v159
	v_exp_f32_e32 v163, v163
	v_add_f32_e32 v143, 1.0, v143
	v_add_f32_e32 v151, 1.0, v151
	v_rcp_f32_e32 v143, v143
	v_add_f32_e32 v147, 1.0, v147
	v_rcp_f32_e32 v151, v151
	v_add_f32_e32 v155, 1.0, v155
	v_add_f32_e32 v157, 1.0, v157
	v_add_f32_e32 v161, 1.0, v161
	v_rcp_f32_e32 v147, v147
	v_rcp_f32_e32 v155, v155
	v_rcp_f32_e32 v157, v157
	v_add_f32_e32 v159, 1.0, v159
	v_rcp_f32_e32 v161, v161
	v_add_f32_e32 v163, 1.0, v163
	v_rcp_f32_e32 v159, v159
	v_rcp_f32_e32 v163, v163
	v_fma_f32 v143, v143, s31, 0.5
	v_fma_f32 v151, v151, s31, 0.5
	v_max_f32_e32 v143, 1.0, v143
	v_fma_f32 v147, v147, s31, 0.5
	v_max_f32_e32 v151, 1.0, v151
	v_fma_f32 v155, v155, s31, 0.5
	v_fma_f32 v157, v157, s31, 0.5
	v_fma_f32 v161, v161, s31, 0.5
	v_cvt_u32_f32_e32 v143, v143
	v_max_f32_e32 v147, 1.0, v147
	v_cvt_u32_f32_e32 v151, v151
	v_max_f32_e32 v155, 1.0, v155
	v_max_f32_e32 v157, 1.0, v157
	v_fma_f32 v159, v159, s31, 0.5
	v_max_f32_e32 v161, 1.0, v161
	v_fma_f32 v163, v163, s31, 0.5
	v_cvt_u32_f32_e32 v147, v147
	v_cvt_u32_f32_e32 v155, v155
	v_cvt_u32_f32_sdwa v157, v157 dst_sel:WORD_1 dst_unused:UNUSED_PAD src0_sel:DWORD
	v_max_f32_e32 v159, 1.0, v159
	v_cvt_u32_f32_sdwa v161, v161 dst_sel:BYTE_3 dst_unused:UNUSED_PAD src0_sel:DWORD
	v_max_f32_e32 v163, 1.0, v163
	v_cvt_u32_f32_sdwa v159, v159 dst_sel:WORD_1 dst_unused:UNUSED_PAD src0_sel:DWORD
	v_cvt_u32_f32_sdwa v163, v163 dst_sel:BYTE_3 dst_unused:UNUSED_PAD src0_sel:DWORD
	v_lshl_add_u64 v[174:175], s[22:23], 0, v[174:175]
	v_lshl_add_u64 v[174:175], v[174:175], 0, v[172:173]
	v_lshl_or_b32 v143, v151, 8, v143
	global_store_dwordx2 v[174:175], v[176:177], off
	v_or3_b32 v176, v143, v157, v161
	v_lshl_or_b32 v143, v155, 8, v147
	v_or3_b32 v177, v143, v159, v163
	s_mov_b64 s[22:23], 0
	global_store_dwordx2 v[174:175], v[176:177], off offset:128
	s_branch .LBB0_674

.LBB0_674:
	v_readlane_b32 s54, v254, 52
	s_andn2_b64 vcc, exec, s[22:23]
	v_readlane_b32 s55, v254, 53
	s_cbranch_vccnz .LBB0_660
	v_mov_b64_e32 v[174:175], s[82:83]
	s_movk_i32 s11, 0x3800
	v_mad_i64_i32 v[176:177], s[22:23], v168, s11, v[174:175]
	v_lshlrev_b64 v[168:169], 1, v[172:173]
	v_lshl_add_u64 v[172:173], v[176:177], 0, v[168:169]
	v_pk_mul_f32 v[128:129], v[128:129], v[170:171] op_sel_hi:[1,0]
	v_pk_mul_f32 v[126:127], v[126:127], v[170:171] op_sel_hi:[1,0]
	v_pk_mul_f32 v[176:177], v[124:125], v[170:171] op_sel_hi:[1,0]
	v_pk_mul_f32 v[124:125], v[122:123], v[170:171] op_sel_hi:[1,0]
	v_cvt_pk_bf16_f32 v122, v126, v127
	v_cvt_pk_bf16_f32 v123, v128, v129
	v_cvt_pk_bf16_f32 v124, v124, v125
	v_cvt_pk_bf16_f32 v125, v176, v177
	global_store_dwordx4 v[172:173], v[122:125], off
	v_pk_mul_f32 v[116:117], v[116:117], v[170:171] op_sel_hi:[1,0]
	v_pk_mul_f32 v[114:115], v[114:115], v[170:171] op_sel_hi:[1,0]
	v_pk_mul_f32 v[122:123], v[108:109], v[170:171] op_sel_hi:[1,0]
	v_pk_mul_f32 v[108:109], v[106:107], v[170:171] op_sel_hi:[1,0]
	v_cvt_pk_bf16_f32 v106, v114, v115
	v_cvt_pk_bf16_f32 v107, v116, v117
	v_cvt_pk_bf16_f32 v108, v108, v109
	v_cvt_pk_bf16_f32 v109, v122, v123
	global_store_dwordx4 v[172:173], v[106:109], off offset:256
	v_pk_mul_f32 v[112:113], v[112:113], v[166:167] op_sel_hi:[1,0]
	v_pk_mul_f32 v[110:111], v[110:111], v[166:167] op_sel_hi:[1,0]
	v_mad_i64_i32 v[106:107], s[22:23], v164, s11, v[174:175]
	v_lshl_add_u64 v[114:115], v[106:107], 0, v[168:169]
	v_pk_mul_f32 v[108:109], v[120:121], v[166:167] op_sel_hi:[1,0]
	v_pk_mul_f32 v[106:107], v[118:119], v[166:167] op_sel_hi:[1,0]
	v_pk_mul_f32 v[100:101], v[100:101], v[166:167] op_sel_hi:[1,0]
	v_cvt_pk_bf16_f32 v106, v106, v107
	v_cvt_pk_bf16_f32 v107, v108, v109
	v_cvt_pk_bf16_f32 v108, v110, v111
	v_cvt_pk_bf16_f32 v109, v112, v113
	global_store_dwordx4 v[114:115], v[106:109], off
	v_pk_mul_f32 v[98:99], v[98:99], v[166:167] op_sel_hi:[1,0]
	v_pk_mul_f32 v[96:97], v[96:97], v[162:163] op_sel_hi:[1,0]
	v_pk_mul_f32 v[106:107], v[92:93], v[166:167] op_sel_hi:[1,0]
	v_pk_mul_f32 v[92:93], v[90:91], v[166:167] op_sel_hi:[1,0]
	v_cvt_pk_bf16_f32 v90, v98, v99
	v_cvt_pk_bf16_f32 v91, v100, v101
	v_cvt_pk_bf16_f32 v92, v92, v93
	v_cvt_pk_bf16_f32 v93, v106, v107
	global_store_dwordx4 v[114:115], v[90:93], off offset:256
	v_pk_mul_f32 v[94:95], v[94:95], v[162:163] op_sel_hi:[1,0]
	v_pk_mul_f32 v[84:85], v[84:85], v[162:163] op_sel_hi:[1,0]
	v_mad_i64_i32 v[90:91], s[22:23], v160, s11, v[174:175]
	v_lshl_add_u64 v[98:99], v[90:91], 0, v[168:169]
	v_pk_mul_f32 v[92:93], v[104:105], v[162:163] op_sel_hi:[1,0]
	v_pk_mul_f32 v[90:91], v[102:103], v[162:163] op_sel_hi:[1,0]
	v_pk_mul_f32 v[82:83], v[82:83], v[162:163] op_sel_hi:[1,0]
	v_cvt_pk_bf16_f32 v90, v90, v91
	v_cvt_pk_bf16_f32 v91, v92, v93
	v_cvt_pk_bf16_f32 v92, v94, v95
	v_cvt_pk_bf16_f32 v93, v96, v97
	global_store_dwordx4 v[98:99], v[90:93], off
	v_pk_mul_f32 v[80:81], v[80:81], v[158:159] op_sel_hi:[1,0]
	v_pk_mul_f32 v[78:79], v[78:79], v[158:159] op_sel_hi:[1,0]
	v_pk_mul_f32 v[90:91], v[76:77], v[162:163] op_sel_hi:[1,0]
	v_pk_mul_f32 v[76:77], v[74:75], v[162:163] op_sel_hi:[1,0]
	v_cvt_pk_bf16_f32 v74, v82, v83
	v_cvt_pk_bf16_f32 v75, v84, v85
	v_cvt_pk_bf16_f32 v76, v76, v77
	v_cvt_pk_bf16_f32 v77, v90, v91
	global_store_dwordx4 v[98:99], v[74:77], off offset:256
	v_pk_mul_f32 v[72:73], v[72:73], v[158:159] op_sel_hi:[1,0]
	v_pk_mul_f32 v[70:71], v[70:71], v[158:159] op_sel_hi:[1,0]
	v_mad_i64_i32 v[74:75], s[22:23], v154, s11, v[174:175]
	v_lshl_add_u64 v[82:83], v[74:75], 0, v[168:169]
	v_pk_mul_f32 v[76:77], v[88:89], v[158:159] op_sel_hi:[1,0]
	v_pk_mul_f32 v[74:75], v[86:87], v[158:159] op_sel_hi:[1,0]
	v_pk_mul_f32 v[64:65], v[64:65], v[152:153] op_sel_hi:[1,0]
	v_cvt_pk_bf16_f32 v74, v74, v75
	v_cvt_pk_bf16_f32 v75, v76, v77
	v_cvt_pk_bf16_f32 v76, v78, v79
	v_cvt_pk_bf16_f32 v77, v80, v81
	global_store_dwordx4 v[82:83], v[74:77], off
	v_pk_mul_f32 v[62:63], v[62:63], v[152:153] op_sel_hi:[1,0]
	v_pk_mul_f32 v[52:53], v[52:53], v[152:153] op_sel_hi:[1,0]
	v_pk_mul_f32 v[74:75], v[68:69], v[158:159] op_sel_hi:[1,0]
	v_pk_mul_f32 v[68:69], v[66:67], v[158:159] op_sel_hi:[1,0]
	v_cvt_pk_bf16_f32 v66, v70, v71
	v_cvt_pk_bf16_f32 v67, v72, v73
	v_cvt_pk_bf16_f32 v68, v68, v69
	v_cvt_pk_bf16_f32 v69, v74, v75
	global_store_dwordx4 v[82:83], v[66:69], off offset:256
	v_pk_mul_f32 v[50:51], v[50:51], v[152:153] op_sel_hi:[1,0]
	v_pk_mul_f32 v[48:49], v[48:49], v[148:149] op_sel_hi:[1,0]
	v_mad_i64_i32 v[66:67], s[22:23], v156, s11, v[174:175]
	v_pk_mul_f32 v[68:69], v[60:61], v[152:153] op_sel_hi:[1,0]
	v_pk_mul_f32 v[60:61], v[58:59], v[152:153] op_sel_hi:[1,0]
	v_lshl_add_u64 v[66:67], v[66:67], 0, v[168:169]
	v_cvt_pk_bf16_f32 v58, v62, v63
	v_cvt_pk_bf16_f32 v59, v64, v65
	v_cvt_pk_bf16_f32 v60, v60, v61
	v_cvt_pk_bf16_f32 v61, v68, v69
	global_store_dwordx4 v[66:67], v[58:61], off
	v_pk_mul_f32 v[46:47], v[46:47], v[148:149] op_sel_hi:[1,0]
	v_pk_mul_f32 v[36:37], v[36:37], v[148:149] op_sel_hi:[1,0]
	v_pk_mul_f32 v[58:59], v[44:45], v[152:153] op_sel_hi:[1,0]
	v_pk_mul_f32 v[44:45], v[42:43], v[152:153] op_sel_hi:[1,0]
	v_cvt_pk_bf16_f32 v42, v50, v51
	v_cvt_pk_bf16_f32 v43, v52, v53
	v_cvt_pk_bf16_f32 v44, v44, v45
	v_cvt_pk_bf16_f32 v45, v58, v59
	global_store_dwordx4 v[66:67], v[42:45], off offset:256
	v_pk_mul_f32 v[34:35], v[34:35], v[148:149] op_sel_hi:[1,0]
	v_pk_mul_f32 v[32:33], v[32:33], v[144:145] op_sel_hi:[1,0]
	v_mad_i64_i32 v[42:43], s[22:23], v150, s11, v[174:175]
	v_lshl_add_u64 v[50:51], v[42:43], 0, v[168:169]
	v_pk_mul_f32 v[44:45], v[56:57], v[148:149] op_sel_hi:[1,0]
	v_pk_mul_f32 v[42:43], v[54:55], v[148:149] op_sel_hi:[1,0]
	v_pk_mul_f32 v[30:31], v[30:31], v[144:145] op_sel_hi:[1,0]
	v_cvt_pk_bf16_f32 v42, v42, v43
	v_cvt_pk_bf16_f32 v43, v44, v45
	v_cvt_pk_bf16_f32 v44, v46, v47
	v_cvt_pk_bf16_f32 v45, v48, v49
	global_store_dwordx4 v[50:51], v[42:45], off
	v_pk_mul_f32 v[20:21], v[20:21], v[144:145] op_sel_hi:[1,0]
	v_pk_mul_f32 v[18:19], v[18:19], v[144:145] op_sel_hi:[1,0]
	v_pk_mul_f32 v[42:43], v[28:29], v[148:149] op_sel_hi:[1,0]
	v_pk_mul_f32 v[28:29], v[26:27], v[148:149] op_sel_hi:[1,0]
	v_cvt_pk_bf16_f32 v26, v34, v35
	v_cvt_pk_bf16_f32 v27, v36, v37
	v_cvt_pk_bf16_f32 v28, v28, v29
	v_cvt_pk_bf16_f32 v29, v42, v43
	global_store_dwordx4 v[50:51], v[26:29], off offset:256
	v_pk_mul_f32 v[14:15], v[14:15], v[140:141] op_sel_hi:[1,0]
	v_pk_mul_f32 v[12:13], v[12:13], v[140:141] op_sel_hi:[1,0]
	v_mad_i64_i32 v[26:27], s[22:23], v146, s11, v[174:175]
	v_lshl_add_u64 v[34:35], v[26:27], 0, v[168:169]
	v_pk_mul_f32 v[28:29], v[40:41], v[144:145] op_sel_hi:[1,0]
	v_pk_mul_f32 v[26:27], v[38:39], v[144:145] op_sel_hi:[1,0]
	v_pk_mul_f32 v[6:7], v[6:7], v[140:141] op_sel_hi:[1,0]
	v_cvt_pk_bf16_f32 v26, v26, v27
	v_cvt_pk_bf16_f32 v27, v28, v29
	v_cvt_pk_bf16_f32 v28, v30, v31
	v_cvt_pk_bf16_f32 v29, v32, v33
	global_store_dwordx4 v[34:35], v[26:29], off
	v_pk_mul_f32 v[4:5], v[4:5], v[140:141] op_sel_hi:[1,0]
	s_nop 0
	v_pk_mul_f32 v[26:27], v[10:11], v[144:145] op_sel_hi:[1,0]
	v_pk_mul_f32 v[10:11], v[8:9], v[144:145] op_sel_hi:[1,0]
	v_cvt_pk_bf16_f32 v8, v18, v19
	v_cvt_pk_bf16_f32 v9, v20, v21
	v_cvt_pk_bf16_f32 v10, v10, v11
	v_cvt_pk_bf16_f32 v11, v26, v27
	global_store_dwordx4 v[34:35], v[8:11], off offset:256
	s_nop 1
	v_mad_i64_i32 v[8:9], s[22:23], v142, s11, v[174:175]
	v_lshl_add_u64 v[18:19], v[8:9], 0, v[168:169]
	v_pk_mul_f32 v[10:11], v[24:25], v[140:141] op_sel_hi:[1,0]
	v_pk_mul_f32 v[8:9], v[22:23], v[140:141] op_sel_hi:[1,0]
	s_nop 0
	v_cvt_pk_bf16_f32 v8, v8, v9
	v_cvt_pk_bf16_f32 v9, v10, v11
	v_cvt_pk_bf16_f32 v10, v12, v13
	v_cvt_pk_bf16_f32 v11, v14, v15
	global_store_dwordx4 v[18:19], v[8:11], off
	s_nop 1
	v_pk_mul_f32 v[8:9], v[2:3], v[140:141] op_sel_hi:[1,0]
	v_pk_mul_f32 v[2:3], v[0:1], v[140:141] op_sel_hi:[1,0]
	v_cvt_pk_bf16_f32 v0, v4, v5
	v_cvt_pk_bf16_f32 v1, v6, v7
	v_cvt_pk_bf16_f32 v2, v2, v3
	v_cvt_pk_bf16_f32 v3, v8, v9
	global_store_dwordx4 v[18:19], v[0:3], off offset:256
	s_branch .LBB0_660

.LBB0_998:
	v_mov_b32_e32 v18, v86
	v_mov_b32_e32 v43, v17
	v_ashrrev_i32_e32 v16, 31, v18
	v_lshrrev_b32_e32 v16, 29, v16
	v_add_u32_e32 v16, v18, v16
	v_lshrrev_b32_e32 v19, 3, v16
	v_and_b32_e32 v16, 0x1ffffff8, v16
	v_sub_u32_e32 v16, v18, v16
	v_lshlrev_b32_e32 v32, 3, v16
	v_lshrrev_b32_e32 v16, 3, v18
	v_mul_lo_u32 v33, v16, s60
	v_lshlrev_b32_e32 v16, 3, v18
	v_and_b32_e32 v34, 56, v16
	v_and_b32_e32 v16, 0x78, v16
	v_or_b32_e32 v16, s12, v16
	v_lshrrev_b32_e32 v36, 4, v18
	v_mad_u64_u32 v[40:41], s[0:1], v36, s60, v[16:17]
	v_add_u32_e32 v36, 0x200, v18
	v_lshrrev_b32_e32 v36, 4, v36
	v_mad_u64_u32 v[48:49], s[0:1], v36, s60, v[16:17]
	v_mul_lo_u32 v19, v19, s60
	s_add_u32 s0, s82, s4
	v_add_u32_e32 v35, s13, v33
	v_add3_u32 v16, v19, s11, v32
	v_add_u32_e32 v19, s16, v33
	s_addc_u32 s1, s83, s5
	v_or_b32_e32 v32, v19, v34
	v_or_b32_e32 v42, v35, v34
	v_lshl_add_u64 v[34:35], v[16:17], 1, s[0:1]
	v_add_co_u32_e32 v34, vcc, s35, v34
	v_mov_b32_e32 v33, v17
	s_nop 0
	v_addc_co_u32_e32 v35, vcc, 0, v35, vcc
	v_lshl_add_u64 v[32:33], v[32:33], 1, s[0:1]
	v_add_co_u32_e32 v36, vcc, s35, v32
	v_lshl_add_u64 v[42:43], v[42:43], 1, s[0:1]
	s_nop 0
	v_addc_co_u32_e32 v37, vcc, 0, v33, vcc
	v_add_co_u32_e32 v42, vcc, s35, v42
	v_mov_b32_e32 v41, v17
	s_nop 0
	v_addc_co_u32_e32 v43, vcc, 0, v43, vcc
	v_lshl_add_u64 v[40:41], v[40:41], 1, s[0:1]
	v_add_co_u32_e32 v44, vcc, 0x380000, v40
	v_mov_b32_e32 v49, v17
	s_nop 0
	v_addc_co_u32_e32 v45, vcc, 0, v41, vcc
	v_lshl_add_u64 v[48:49], v[48:49], 1, s[0:1]
	v_add_co_u32_e32 v48, vcc, 0x380000, v48
	global_load_dwordx4 v[32:35], v[34:35], off
	s_nop 0
	global_load_dwordx4 v[36:39], v[36:37], off
	v_addc_co_u32_e32 v49, vcc, 0, v49, vcc
	global_load_dwordx4 v[40:43], v[42:43], off
	s_nop 0
	global_load_dwordx4 v[44:47], v[44:45], off
	v_cmp_gt_i32_e32 vcc, 48, v18
	global_load_dwordx4 v[48:51], v[48:49], off
	s_and_saveexec_b64 s[0:1], vcc
	s_cbranch_execz .LBB0_981
	v_lshlrev_b32_e32 v18, 2, v18
	s_add_u32 s8, s82, s10
	v_ashrrev_i32_e32 v19, 31, v18
	s_addc_u32 s9, s83, s2
	v_lshl_add_u64 v[18:19], v[18:19], 2, s[8:9]
	v_add_co_u32_e32 v18, vcc, 0x1f7c0000, v18
	s_nop 1
	v_addc_co_u32_e32 v19, vcc, 0, v19, vcc
	global_load_dwordx4 v[28:31], v[18:19], off offset:3072
	s_branch .LBB0_981
.Lgla_done:
	s_branch .LBB0_1000
.LBB0_1000:
	s_mov_b64 s[0:1], 0

.LBB0_1038:
	s_cmp_lt_u32 s50, 32
	s_cbranch_scc0 .Llru_hg_skip
	v_readfirstlane_b32 s2, v232
	s_cmp_lt_u32 s2, 64
	s_cbranch_scc0 .Llru_hg_skip
	s_lshr_b32 s96, s50, 3
	s_lshl_b64 s[0:1], s[96:97], 18
	v_readlane_b32 s2, v252, 44
	s_add_u32 s0, s2, s0
	v_readlane_b32 s2, v252, 45
	s_addc_u32 s1, s2, s1
	s_lshl_b64 s[4:5], s[96:97], 17
	v_readlane_b32 s2, v252, 46
	s_add_u32 s4, s2, s4
	v_readlane_b32 s2, v252, 47
	s_addc_u32 s5, s2, s5
	s_and_b32 s2, s50, 7
	s_lshl_b32 s2, s2, 6
	v_add_u32_e32 v1, s2, v232
	v_lshlrev_b32_e32 v0, 3, v1
	v_lshlrev_b32_e32 v1, 2, v1
	global_load_dwordx2 v[20:21], v0, s[0:1]
	v_add_u32_e32 v0, 0x1000, v0
	global_load_dwordx2 v[22:23], v0, s[0:1]
	v_add_u32_e32 v0, 0x1000, v0
	global_load_dwordx2 v[24:25], v0, s[0:1]
	v_add_u32_e32 v0, 0x1000, v0
	global_load_dwordx2 v[26:27], v0, s[0:1]
	v_add_u32_e32 v0, 0x1000, v0
	global_load_dwordx2 v[28:29], v0, s[0:1]
	v_add_u32_e32 v0, 0x1000, v0
	global_load_dwordx2 v[30:31], v0, s[0:1]
	v_add_u32_e32 v0, 0x1000, v0
	global_load_dwordx2 v[32:33], v0, s[0:1]
	v_add_u32_e32 v0, 0x1000, v0
	global_load_dwordx2 v[34:35], v0, s[0:1]
	v_add_u32_e32 v0, 0x1000, v0
	global_load_dwordx2 v[36:37], v0, s[0:1]
	v_add_u32_e32 v0, 0x1000, v0
	global_load_dwordx2 v[38:39], v0, s[0:1]
	v_add_u32_e32 v0, 0x1000, v0
	global_load_dwordx2 v[40:41], v0, s[0:1]
	v_add_u32_e32 v0, 0x1000, v0
	global_load_dwordx2 v[42:43], v0, s[0:1]
	v_add_u32_e32 v0, 0x1000, v0
	global_load_dwordx2 v[44:45], v0, s[0:1]
	v_add_u32_e32 v0, 0x1000, v0
	global_load_dwordx2 v[46:47], v0, s[0:1]
	v_add_u32_e32 v0, 0x1000, v0
	global_load_dwordx2 v[48:49], v0, s[0:1]
	v_add_u32_e32 v0, 0x1000, v0
	global_load_dwordx2 v[50:51], v0, s[0:1]
	v_add_u32_e32 v0, 0x1000, v0
	global_load_dwordx2 v[52:53], v0, s[0:1]
	v_add_u32_e32 v0, 0x1000, v0
	global_load_dwordx2 v[54:55], v0, s[0:1]
	v_add_u32_e32 v0, 0x1000, v0
	global_load_dwordx2 v[56:57], v0, s[0:1]
	v_add_u32_e32 v0, 0x1000, v0
	global_load_dwordx2 v[58:59], v0, s[0:1]
	v_add_u32_e32 v0, 0x1000, v0
	global_load_dwordx2 v[60:61], v0, s[0:1]
	v_add_u32_e32 v0, 0x1000, v0
	global_load_dwordx2 v[62:63], v0, s[0:1]
	v_add_u32_e32 v0, 0x1000, v0
	global_load_dwordx2 v[64:65], v0, s[0:1]
	v_add_u32_e32 v0, 0x1000, v0
	global_load_dwordx2 v[66:67], v0, s[0:1]
	v_add_u32_e32 v0, 0x1000, v0
	global_load_dwordx2 v[68:69], v0, s[0:1]
	v_add_u32_e32 v0, 0x1000, v0
	global_load_dwordx2 v[70:71], v0, s[0:1]
	v_add_u32_e32 v0, 0x1000, v0
	global_load_dwordx2 v[72:73], v0, s[0:1]
	v_add_u32_e32 v0, 0x1000, v0
	global_load_dwordx2 v[74:75], v0, s[0:1]
	v_add_u32_e32 v0, 0x1000, v0
	global_load_dwordx2 v[76:77], v0, s[0:1]
	v_add_u32_e32 v0, 0x1000, v0
	global_load_dwordx2 v[78:79], v0, s[0:1]
	v_add_u32_e32 v0, 0x1000, v0
	global_load_dwordx2 v[80:81], v0, s[0:1]
	v_add_u32_e32 v0, 0x1000, v0
	global_load_dwordx2 v[82:83], v0, s[0:1]
	v_add_u32_e32 v0, 0x1000, v0
	global_load_dwordx2 v[84:85], v0, s[0:1]
	v_add_u32_e32 v0, 0x1000, v0
	global_load_dwordx2 v[86:87], v0, s[0:1]
	v_add_u32_e32 v0, 0x1000, v0
	global_load_dwordx2 v[88:89], v0, s[0:1]
	v_add_u32_e32 v0, 0x1000, v0
	global_load_dwordx2 v[90:91], v0, s[0:1]
	v_add_u32_e32 v0, 0x1000, v0
	global_load_dwordx2 v[92:93], v0, s[0:1]
	v_add_u32_e32 v0, 0x1000, v0
	global_load_dwordx2 v[94:95], v0, s[0:1]
	v_add_u32_e32 v0, 0x1000, v0
	global_load_dwordx2 v[96:97], v0, s[0:1]
	v_add_u32_e32 v0, 0x1000, v0
	global_load_dwordx2 v[98:99], v0, s[0:1]
	v_add_u32_e32 v0, 0x1000, v0
	global_load_dwordx2 v[100:101], v0, s[0:1]
	v_add_u32_e32 v0, 0x1000, v0
	global_load_dwordx2 v[102:103], v0, s[0:1]
	v_add_u32_e32 v0, 0x1000, v0
	global_load_dwordx2 v[104:105], v0, s[0:1]
	v_add_u32_e32 v0, 0x1000, v0
	global_load_dwordx2 v[106:107], v0, s[0:1]
	v_add_u32_e32 v0, 0x1000, v0
	global_load_dwordx2 v[108:109], v0, s[0:1]
	v_add_u32_e32 v0, 0x1000, v0
	global_load_dwordx2 v[110:111], v0, s[0:1]
	v_add_u32_e32 v0, 0x1000, v0
	global_load_dwordx2 v[112:113], v0, s[0:1]
	v_add_u32_e32 v0, 0x1000, v0
	global_load_dwordx2 v[114:115], v0, s[0:1]
	v_add_u32_e32 v0, 0x1000, v0
	global_load_dwordx2 v[116:117], v0, s[0:1]
	v_add_u32_e32 v0, 0x1000, v0
	global_load_dwordx2 v[118:119], v0, s[0:1]
	v_add_u32_e32 v0, 0x1000, v0
	global_load_dwordx2 v[120:121], v0, s[0:1]
	v_add_u32_e32 v0, 0x1000, v0
	global_load_dwordx2 v[122:123], v0, s[0:1]
	v_add_u32_e32 v0, 0x1000, v0
	global_load_dwordx2 v[124:125], v0, s[0:1]
	v_add_u32_e32 v0, 0x1000, v0
	global_load_dwordx2 v[126:127], v0, s[0:1]
	v_add_u32_e32 v0, 0x1000, v0
	global_load_dwordx2 v[128:129], v0, s[0:1]
	v_add_u32_e32 v0, 0x1000, v0
	global_load_dwordx2 v[130:131], v0, s[0:1]
	v_add_u32_e32 v0, 0x1000, v0
	global_load_dwordx2 v[132:133], v0, s[0:1]
	v_add_u32_e32 v0, 0x1000, v0
	global_load_dwordx2 v[134:135], v0, s[0:1]
	v_add_u32_e32 v0, 0x1000, v0
	global_load_dwordx2 v[136:137], v0, s[0:1]
	v_add_u32_e32 v0, 0x1000, v0
	global_load_dwordx2 v[138:139], v0, s[0:1]
	v_add_u32_e32 v0, 0x1000, v0
	global_load_dwordx2 v[140:141], v0, s[0:1]
	v_add_u32_e32 v0, 0x1000, v0
	global_load_dwordx2 v[142:143], v0, s[0:1]
	v_add_u32_e32 v0, 0x1000, v0
	v_mov_b32_e32 v2, 0
	s_waitcnt vmcnt(60)
	v_fmac_f32_e32 v21, v20, v2
	v_fmac_f32_e32 v23, v22, v21
	global_load_dwordx2 v[144:145], v0, s[0:1]
	v_add_u32_e32 v0, 0x1000, v0
	global_load_dwordx2 v[146:147], v0, s[0:1]
	v_add_u32_e32 v0, 0x1000, v0
	s_waitcnt vmcnt(61)
	v_fmac_f32_e32 v25, v24, v23
	s_waitcnt vmcnt(60)
	v_fmac_f32_e32 v27, v26, v25
	s_waitcnt vmcnt(59)
	v_fmac_f32_e32 v29, v28, v27
	s_waitcnt vmcnt(58)
	v_fmac_f32_e32 v31, v30, v29
	s_waitcnt vmcnt(57)
	v_fmac_f32_e32 v33, v32, v31
	s_waitcnt vmcnt(56)
	v_fmac_f32_e32 v35, v34, v33
	s_waitcnt vmcnt(55)
	v_fmac_f32_e32 v37, v36, v35
	s_waitcnt vmcnt(54)
	v_fmac_f32_e32 v39, v38, v37
	s_waitcnt vmcnt(53)
	v_fmac_f32_e32 v41, v40, v39
	s_waitcnt vmcnt(52)
	v_fmac_f32_e32 v43, v42, v41
	s_waitcnt vmcnt(51)
	v_fmac_f32_e32 v45, v44, v43
	s_waitcnt vmcnt(50)
	v_fmac_f32_e32 v47, v46, v45
	s_waitcnt vmcnt(49)
	v_fmac_f32_e32 v49, v48, v47
	s_waitcnt vmcnt(48)
	v_fmac_f32_e32 v51, v50, v49
	s_waitcnt vmcnt(47)
	v_fmac_f32_e32 v53, v52, v51
	s_waitcnt vmcnt(46)
	v_fmac_f32_e32 v55, v54, v53
	s_waitcnt vmcnt(45)
	v_fmac_f32_e32 v57, v56, v55
	s_waitcnt vmcnt(44)
	v_fmac_f32_e32 v59, v58, v57
	s_waitcnt vmcnt(43)
	v_fmac_f32_e32 v61, v60, v59
	s_waitcnt vmcnt(42)
	v_fmac_f32_e32 v63, v62, v61
	s_waitcnt vmcnt(41)
	v_fmac_f32_e32 v65, v64, v63
	s_waitcnt vmcnt(40)
	v_fmac_f32_e32 v67, v66, v65
	s_waitcnt vmcnt(39)
	v_fmac_f32_e32 v69, v68, v67
	s_waitcnt vmcnt(38)
	v_fmac_f32_e32 v71, v70, v69
	s_waitcnt vmcnt(37)
	v_fmac_f32_e32 v73, v72, v71
	s_waitcnt vmcnt(36)
	v_fmac_f32_e32 v75, v74, v73
	s_waitcnt vmcnt(35)
	v_fmac_f32_e32 v77, v76, v75
	s_waitcnt vmcnt(34)
	v_fmac_f32_e32 v79, v78, v77
	s_waitcnt vmcnt(33)
	v_fmac_f32_e32 v81, v80, v79
	s_waitcnt vmcnt(32)
	v_fmac_f32_e32 v83, v82, v81
	s_waitcnt vmcnt(31)
	v_fmac_f32_e32 v85, v84, v83
	s_waitcnt vmcnt(30)
	v_fmac_f32_e32 v87, v86, v85
	s_waitcnt vmcnt(29)
	v_fmac_f32_e32 v89, v88, v87
	s_waitcnt vmcnt(28)
	v_fmac_f32_e32 v91, v90, v89
	s_waitcnt vmcnt(27)
	v_fmac_f32_e32 v93, v92, v91
	s_waitcnt vmcnt(26)
	v_fmac_f32_e32 v95, v94, v93
	s_waitcnt vmcnt(25)
	v_fmac_f32_e32 v97, v96, v95
	s_waitcnt vmcnt(24)
	v_fmac_f32_e32 v99, v98, v97
	s_waitcnt vmcnt(23)
	v_fmac_f32_e32 v101, v100, v99
	s_waitcnt vmcnt(22)
	v_fmac_f32_e32 v103, v102, v101
	s_waitcnt vmcnt(21)
	v_fmac_f32_e32 v105, v104, v103
	s_waitcnt vmcnt(20)
	v_fmac_f32_e32 v107, v106, v105
	s_waitcnt vmcnt(19)
	v_fmac_f32_e32 v109, v108, v107
	s_waitcnt vmcnt(18)
	v_fmac_f32_e32 v111, v110, v109
	s_waitcnt vmcnt(17)
	v_fmac_f32_e32 v113, v112, v111
	s_waitcnt vmcnt(16)
	v_fmac_f32_e32 v115, v114, v113
	s_waitcnt vmcnt(15)
	v_fmac_f32_e32 v117, v116, v115
	s_waitcnt vmcnt(14)
	v_fmac_f32_e32 v119, v118, v117
	s_waitcnt vmcnt(13)
	v_fmac_f32_e32 v121, v120, v119
	s_waitcnt vmcnt(12)
	v_fmac_f32_e32 v123, v122, v121
	s_waitcnt vmcnt(11)
	v_fmac_f32_e32 v125, v124, v123
	s_waitcnt vmcnt(10)
	v_fmac_f32_e32 v127, v126, v125
	s_waitcnt vmcnt(9)
	v_fmac_f32_e32 v129, v128, v127
	s_waitcnt vmcnt(8)
	v_fmac_f32_e32 v131, v130, v129
	s_waitcnt vmcnt(7)
	v_fmac_f32_e32 v133, v132, v131
	s_waitcnt vmcnt(6)
	v_fmac_f32_e32 v135, v134, v133
	s_waitcnt vmcnt(5)
	v_fmac_f32_e32 v137, v136, v135
	s_waitcnt vmcnt(4)
	v_fmac_f32_e32 v139, v138, v137
	s_waitcnt vmcnt(3)
	v_fmac_f32_e32 v141, v140, v139
	s_waitcnt vmcnt(2)
	v_fmac_f32_e32 v143, v142, v141
	s_waitcnt vmcnt(1)
	v_fmac_f32_e32 v145, v144, v143
	s_waitcnt vmcnt(0)
	v_fmac_f32_e32 v147, v146, v145
	global_store_dword v1, v2, s[4:5]
	v_add_u32_e32 v1, 0x800, v1
	global_store_dword v1, v21, s[4:5]
	v_add_u32_e32 v1, 0x800, v1
	global_store_dword v1, v23, s[4:5]
	v_add_u32_e32 v1, 0x800, v1
	global_store_dword v1, v25, s[4:5]
	v_add_u32_e32 v1, 0x800, v1
	global_store_dword v1, v27, s[4:5]
	v_add_u32_e32 v1, 0x800, v1
	global_store_dword v1, v29, s[4:5]
	v_add_u32_e32 v1, 0x800, v1
	global_store_dword v1, v31, s[4:5]
	v_add_u32_e32 v1, 0x800, v1
	global_store_dword v1, v33, s[4:5]
	v_add_u32_e32 v1, 0x800, v1
	global_store_dword v1, v35, s[4:5]
	v_add_u32_e32 v1, 0x800, v1
	global_store_dword v1, v37, s[4:5]
	v_add_u32_e32 v1, 0x800, v1
	global_store_dword v1, v39, s[4:5]
	v_add_u32_e32 v1, 0x800, v1
	global_store_dword v1, v41, s[4:5]
	v_add_u32_e32 v1, 0x800, v1
	global_store_dword v1, v43, s[4:5]
	v_add_u32_e32 v1, 0x800, v1
	global_store_dword v1, v45, s[4:5]
	v_add_u32_e32 v1, 0x800, v1
	global_store_dword v1, v47, s[4:5]
	v_add_u32_e32 v1, 0x800, v1
	global_store_dword v1, v49, s[4:5]
	v_add_u32_e32 v1, 0x800, v1
	global_store_dword v1, v51, s[4:5]
	v_add_u32_e32 v1, 0x800, v1
	global_store_dword v1, v53, s[4:5]
	v_add_u32_e32 v1, 0x800, v1
	global_store_dword v1, v55, s[4:5]
	v_add_u32_e32 v1, 0x800, v1
	global_store_dword v1, v57, s[4:5]
	v_add_u32_e32 v1, 0x800, v1
	global_store_dword v1, v59, s[4:5]
	v_add_u32_e32 v1, 0x800, v1
	global_store_dword v1, v61, s[4:5]
	v_add_u32_e32 v1, 0x800, v1
	global_store_dword v1, v63, s[4:5]
	v_add_u32_e32 v1, 0x800, v1
	global_store_dword v1, v65, s[4:5]
	v_add_u32_e32 v1, 0x800, v1
	global_store_dword v1, v67, s[4:5]
	v_add_u32_e32 v1, 0x800, v1
	global_store_dword v1, v69, s[4:5]
	v_add_u32_e32 v1, 0x800, v1
	global_store_dword v1, v71, s[4:5]
	v_add_u32_e32 v1, 0x800, v1
	global_store_dword v1, v73, s[4:5]
	v_add_u32_e32 v1, 0x800, v1
	global_store_dword v1, v75, s[4:5]
	v_add_u32_e32 v1, 0x800, v1
	global_store_dword v1, v77, s[4:5]
	v_add_u32_e32 v1, 0x800, v1
	global_store_dword v1, v79, s[4:5]
	v_add_u32_e32 v1, 0x800, v1
	global_store_dword v1, v81, s[4:5]
	v_add_u32_e32 v1, 0x800, v1
	global_store_dword v1, v83, s[4:5]
	v_add_u32_e32 v1, 0x800, v1
	s_waitcnt vmcnt(16)
	global_store_dword v1, v85, s[4:5]
	v_add_u32_e32 v1, 0x800, v1
	global_store_dword v1, v87, s[4:5]
	v_add_u32_e32 v1, 0x800, v1
	global_store_dword v1, v89, s[4:5]
	v_add_u32_e32 v1, 0x800, v1
	global_store_dword v1, v91, s[4:5]
	v_add_u32_e32 v1, 0x800, v1
	global_store_dword v1, v93, s[4:5]
	v_add_u32_e32 v1, 0x800, v1
	global_store_dword v1, v95, s[4:5]
	v_add_u32_e32 v1, 0x800, v1
	global_store_dword v1, v97, s[4:5]
	v_add_u32_e32 v1, 0x800, v1
	global_store_dword v1, v99, s[4:5]
	v_add_u32_e32 v1, 0x800, v1
	global_store_dword v1, v101, s[4:5]
	v_add_u32_e32 v1, 0x800, v1
	global_store_dword v1, v103, s[4:5]
	v_add_u32_e32 v1, 0x800, v1
	global_store_dword v1, v105, s[4:5]
	v_add_u32_e32 v1, 0x800, v1
	global_store_dword v1, v107, s[4:5]
	v_add_u32_e32 v1, 0x800, v1
	global_store_dword v1, v109, s[4:5]
	v_add_u32_e32 v1, 0x800, v1
	global_store_dword v1, v111, s[4:5]
	v_add_u32_e32 v1, 0x800, v1
	global_store_dword v1, v113, s[4:5]
	v_add_u32_e32 v1, 0x800, v1
	global_store_dword v1, v115, s[4:5]
	v_add_u32_e32 v1, 0x800, v1
	global_store_dword v1, v117, s[4:5]
	v_add_u32_e32 v1, 0x800, v1
	global_store_dword v1, v119, s[4:5]
	v_add_u32_e32 v1, 0x800, v1
	global_store_dword v1, v121, s[4:5]
	v_add_u32_e32 v1, 0x800, v1
	global_store_dword v1, v123, s[4:5]
	v_add_u32_e32 v1, 0x800, v1
	global_store_dword v1, v125, s[4:5]
	v_add_u32_e32 v1, 0x800, v1
	global_store_dword v1, v127, s[4:5]
	v_add_u32_e32 v1, 0x800, v1
	global_store_dword v1, v129, s[4:5]
	v_add_u32_e32 v1, 0x800, v1
	global_store_dword v1, v131, s[4:5]
	v_add_u32_e32 v1, 0x800, v1
	global_store_dword v1, v133, s[4:5]
	v_add_u32_e32 v1, 0x800, v1
	global_store_dword v1, v135, s[4:5]
	v_add_u32_e32 v1, 0x800, v1
	global_store_dword v1, v137, s[4:5]
	v_add_u32_e32 v1, 0x800, v1
	global_store_dword v1, v139, s[4:5]
	v_add_u32_e32 v1, 0x800, v1
	global_store_dword v1, v141, s[4:5]
	v_add_u32_e32 v1, 0x800, v1
	global_store_dword v1, v143, s[4:5]
	v_add_u32_e32 v1, 0x800, v1
	global_store_dword v1, v145, s[4:5]
